# v71: redundant-wait elimination - the second s_waitcnt lgkmcnt(0) after each K-loop barrier removed (LDS already drained before the barrier)
# baseline (speedup 1.0000x reference)
; #define PG8_STAGE(bufoff, gbase) do { _Pragma("unroll") for (int _i = 0; _i < 2; ++_i) \
;         __builtin_amdgcn_global_load_lds((const unsigned*)((const char*)(gbase) + voff[_i]), (LAS unsigned*)(lds + (bufoff) + ldsw + _i * 8192), 16, 0, 0); } while (0)
; #define PG8_LDA(dst, b, h) do { _Pragma("unroll") for (int m = 0; m < 4; ++m) _Pragma("unroll") for (int k = 0; k < 2; ++k) dst[m][k] = *(const LAS bf16x8*)(lds + PG8_SA(b, h) + aoff + m * 2048 + k * 1024); } while (0)
; #define PG8_LDB(dst, b, h) do { _Pragma("unroll") for (int n = 0; n < 2; ++n) _Pragma("unroll") for (int k = 0; k < 2; ++k) dst[n][k] = *(const LAS bf16x8*)(lds + PG8_SB(b, h) + boff + n * 2048 + k * 1024); } while (0)
; #define PG8_MMA(ai, bj, At, Bt) do { __builtin_amdgcn_s_setprio(1); _Pragma("unroll") for (int m = 0; m < 4; ++m) _Pragma("unroll") for (int n = 0; n < 2; ++n) _Pragma("unroll") for (int k = 0; k < 2; ++k) \
;         acc[ai][bj][m][n] = __builtin_amdgcn_mfma_f32_16x16x32_bf16(Bt[n][k], At[m][k], acc[ai][bj][m][n], 0, 0, 0); __builtin_amdgcn_s_setprio(0); } while (0)
; #define PG8_WAIT_V(n) asm volatile("s_waitcnt vmcnt(" #n ")" ::: "memory")
; #define PG8_WAIT_L(n) asm volatile("s_waitcnt lgkmcnt(" #n ")" ::: "memory")
; #define PG8_BAR __builtin_amdgcn_s_barrier()
; #define PG8_SCHED __builtin_amdgcn_sched_barrier(0)
; template <int EPI> ...
;     ...
;         for (int t = 0; t < cnk; t += 2) {
;             const bool last = (t == cnk - 2);
;             const char* a1 = cA + (size_t)(t + 1) * kstep;
;             const char* a2 = last ? nA : cA + (size_t)(t + 2) * kstep; const char* b2 = last ? nB : cB + (size_t)(t + 2) * kstep;
;             const char* a3 = a2 + kstep; const char* b3 = b2 + kstep;
;             PG8_LDB(B0, 0, 0); PG8_LDB(B1, 0, 1); PG8_SCHED; PG8_LDA(At, 0, 0); PG8_STAGE(PG8_SA(1, 1), a1 + hstep);
;             PG8_WAIT_V(8); PG8_WAIT_L(0); PG8_BAR; PG8_MMA(0, 0, At, B0); PG8_MMA(0, 1, At, B1); PG8_BAR; PG8_SCHED;
;             PG8_LDA(At, 0, 1); PG8_STAGE(PG8_SB(0, 0), b2); PG8_STAGE(PG8_SB(0, 1), b2 + hstep); PG8_STAGE(PG8_SA(0, 0), a2);
;             PG8_WAIT_V(8); PG8_WAIT_L(0); PG8_BAR; PG8_MMA(1, 0, At, B0); PG8_MMA(1, 1, At, B1); PG8_BAR; PG8_SCHED;
.LBB0_137:
	ds_read_b128 v[130:133], v178
	ds_read_b128 v[164:167], v178 offset:1024
	ds_read_b128 v[168:171], v178 offset:2048
	ds_read_b128 v[172:175], v178 offset:3072
	ds_read_b128 v[188:191], v179
	ds_read_b128 v[192:195], v179 offset:1024
	ds_read_b128 v[196:199], v179 offset:2048
	ds_read_b128 v[200:203], v179 offset:3072
	s_add_u32 s28, s26, 0xfffc0080
	s_addc_u32 s29, s27, -1
	s_cmp_eq_u32 s36, 12
	s_cselect_b32 s31, s5, s29
	s_cselect_b32 s30, s7, s28
	s_cselect_b32 s29, s19, s35
	s_cselect_b32 s28, s21, s34
	v_lshl_add_u64 v[176:177], s[26:27], 0, v[156:157]
	s_add_i32 m0, s42, 0xc000
	ds_read_b128 v[204:207], v180
	ds_read_b128 v[208:211], v180 offset:1024
	ds_read_b128 v[212:215], v180 offset:2048
	ds_read_b128 v[216:219], v180 offset:3072
	ds_read_b128 v[220:223], v180 offset:4096
	ds_read_b128 v[224:227], v180 offset:5120
	ds_read_b128 v[228:231], v180 offset:6144
	ds_read_b128 v[232:235], v180 offset:7168
	global_load_lds_dwordx4 v[176:177], off
	v_lshl_add_u64 v[176:177], s[26:27], 0, v[158:159]
	s_add_i32 m0, s42, 0xe000
	s_nop 0
	global_load_lds_dwordx4 v[176:177], off
	s_waitcnt vmcnt(8)
	s_waitcnt lgkmcnt(0)
	s_barrier
	s_setprio 1
	v_mfma_f32_16x16x32_bf16 v[126:129], v[130:133], v[204:207], v[126:129]
	v_mfma_f32_16x16x32_bf16 v[122:125], v[168:171], v[204:207], v[122:125]
	v_mfma_f32_16x16x32_bf16 v[118:121], v[130:133], v[212:215], v[118:121]
	v_mfma_f32_16x16x32_bf16 v[114:117], v[168:171], v[212:215], v[114:117]
	v_mfma_f32_16x16x32_bf16 v[110:113], v[130:133], v[220:223], v[110:113]
	v_mfma_f32_16x16x32_bf16 v[106:109], v[168:171], v[220:223], v[106:109]
	v_mfma_f32_16x16x32_bf16 v[102:105], v[130:133], v[228:231], v[102:105]
	v_mfma_f32_16x16x32_bf16 v[98:101], v[168:171], v[228:231], v[98:101]
	v_mfma_f32_16x16x32_bf16 v[126:129], v[164:167], v[208:211], v[126:129]
	v_mfma_f32_16x16x32_bf16 v[122:125], v[172:175], v[208:211], v[122:125]
	v_mfma_f32_16x16x32_bf16 v[118:121], v[164:167], v[216:219], v[118:121]
	v_mfma_f32_16x16x32_bf16 v[114:117], v[172:175], v[216:219], v[114:117]
	v_mfma_f32_16x16x32_bf16 v[110:113], v[164:167], v[224:227], v[110:113]
	v_mfma_f32_16x16x32_bf16 v[106:109], v[172:175], v[224:227], v[106:109]
	v_mfma_f32_16x16x32_bf16 v[102:105], v[164:167], v[232:235], v[102:105]
	v_mfma_f32_16x16x32_bf16 v[98:101], v[172:175], v[232:235], v[98:101]
	s_setprio 0
	s_setprio 1
	v_mfma_f32_16x16x32_bf16 v[62:65], v[188:191], v[204:207], v[62:65]
	v_mfma_f32_16x16x32_bf16 v[58:61], v[196:199], v[204:207], v[58:61]
	v_mfma_f32_16x16x32_bf16 v[54:57], v[188:191], v[212:215], v[54:57]
	v_mfma_f32_16x16x32_bf16 v[50:53], v[196:199], v[212:215], v[50:53]
	v_mfma_f32_16x16x32_bf16 v[46:49], v[188:191], v[220:223], v[46:49]
	v_mfma_f32_16x16x32_bf16 v[42:45], v[196:199], v[220:223], v[42:45]
	v_mfma_f32_16x16x32_bf16 v[38:41], v[188:191], v[228:231], v[38:41]
	v_mfma_f32_16x16x32_bf16 v[34:37], v[196:199], v[228:231], v[34:37]
	v_mfma_f32_16x16x32_bf16 v[62:65], v[192:195], v[208:211], v[62:65]
	v_mfma_f32_16x16x32_bf16 v[58:61], v[200:203], v[208:211], v[58:61]
	v_mfma_f32_16x16x32_bf16 v[54:57], v[192:195], v[216:219], v[54:57]
	v_mfma_f32_16x16x32_bf16 v[50:53], v[200:203], v[216:219], v[50:53]
	v_mfma_f32_16x16x32_bf16 v[46:49], v[192:195], v[224:227], v[46:49]
	v_mfma_f32_16x16x32_bf16 v[42:45], v[200:203], v[224:227], v[42:45]
	v_mfma_f32_16x16x32_bf16 v[38:41], v[192:195], v[232:235], v[38:41]
	v_mfma_f32_16x16x32_bf16 v[34:37], v[200:203], v[232:235], v[34:37]
	s_setprio 0
	s_barrier
	s_add_i32 s37, s55, s41
	v_lshl_add_u64 v[176:177], s[28:29], 0, v[136:137]
	s_mov_b32 m0, s37
	ds_read_b128 v[204:207], v180 offset:16384
	ds_read_b128 v[208:211], v180 offset:17408
	ds_read_b128 v[212:215], v180 offset:18432
	ds_read_b128 v[216:219], v180 offset:19456
	ds_read_b128 v[220:223], v180 offset:20480
	ds_read_b128 v[224:227], v180 offset:21504
	ds_read_b128 v[228:231], v180 offset:22528
	ds_read_b128 v[232:235], v180 offset:23552
	global_load_lds_dwordx4 v[176:177], off
	s_add_i32 m0, s37, 0x2000
	s_add_u32 s38, s28, 0x40000
	v_lshl_add_u64 v[236:237], s[28:29], 0, v[138:139]
	s_addc_u32 s39, s29, 0
	s_add_i32 s37, s56, s41
	global_load_lds_dwordx4 v[236:237], off
	v_lshl_add_u64 v[238:239], s[38:39], 0, v[136:137]
	s_mov_b32 m0, s37
	v_lshl_add_u64 v[240:241], s[30:31], 0, v[138:139]
	global_load_lds_dwordx4 v[238:239], off
	v_lshl_add_u64 v[238:239], s[38:39], 0, v[138:139]
	s_add_i32 m0, s37, 0x2000
	s_nop 0
	global_load_lds_dwordx4 v[238:239], off
	v_lshl_add_u64 v[238:239], s[30:31], 0, v[136:137]
	s_mov_b32 m0, s42
	s_nop 0
	global_load_lds_dwordx4 v[238:239], off
	s_mov_b32 m0, s43
	s_nop 0
	global_load_lds_dwordx4 v[240:241], off
	s_waitcnt vmcnt(8)
	s_waitcnt lgkmcnt(0)
	s_barrier
; #define PG8_STAGE(bufoff, gbase) do { _Pragma("unroll") for (int _i = 0; _i < 2; ++_i) \
;         __builtin_amdgcn_global_load_lds((const unsigned*)((const char*)(gbase) + voff[_i]), (LAS unsigned*)(lds + (bufoff) + ldsw + _i * 8192), 16, 0, 0); } while (0)
; #define PG8_LDA(dst, b, h) do { _Pragma("unroll") for (int m = 0; m < 4; ++m) _Pragma("unroll") for (int k = 0; k < 2; ++k) dst[m][k] = *(const LAS bf16x8*)(lds + PG8_SA(b, h) + aoff + m * 2048 + k * 1024); } while (0)
; #define PG8_LDB(dst, b, h) do { _Pragma("unroll") for (int n = 0; n < 2; ++n) _Pragma("unroll") for (int k = 0; k < 2; ++k) dst[n][k] = *(const LAS bf16x8*)(lds + PG8_SB(b, h) + boff + n * 2048 + k * 1024); } while (0)
; #define PG8_MMA(ai, bj, At, Bt) do { __builtin_amdgcn_s_setprio(1); _Pragma("unroll") for (int m = 0; m < 4; ++m) _Pragma("unroll") for (int n = 0; n < 2; ++n) _Pragma("unroll") for (int k = 0; k < 2; ++k) \
;         acc[ai][bj][m][n] = __builtin_amdgcn_mfma_f32_16x16x32_bf16(Bt[n][k], At[m][k], acc[ai][bj][m][n], 0, 0, 0); __builtin_amdgcn_s_setprio(0); } while (0)
; #define PG8_WAIT_V(n) asm volatile("s_waitcnt vmcnt(" #n ")" ::: "memory")
; #define PG8_WAIT_L(n) asm volatile("s_waitcnt lgkmcnt(" #n ")" ::: "memory")
; #define PG8_BAR __builtin_amdgcn_s_barrier()
; #define PG8_SCHED __builtin_amdgcn_sched_barrier(0)
; template <int EPI> ...
;     ...
;             PG8_WAIT_V(8); PG8_WAIT_L(0); PG8_BAR; PG8_MMA(1, 0, At, B0); PG8_MMA(1, 1, At, B1); PG8_BAR; PG8_SCHED;
;             PG8_LDB(B0, 1, 0); PG8_LDB(B1, 1, 1); PG8_SCHED; PG8_LDA(At, 1, 0); PG8_STAGE(PG8_SA(0, 1), a2 + hstep);
;             PG8_WAIT_V(8); PG8_WAIT_L(0); PG8_BAR; PG8_MMA(0, 0, At, B0); PG8_MMA(0, 1, At, B1); PG8_BAR; PG8_SCHED;
	s_setprio 1
	v_mfma_f32_16x16x32_bf16 v[94:97], v[130:133], v[204:207], v[94:97]
	v_mfma_f32_16x16x32_bf16 v[90:93], v[168:171], v[204:207], v[90:93]
	v_mfma_f32_16x16x32_bf16 v[86:89], v[130:133], v[212:215], v[86:89]
	v_mfma_f32_16x16x32_bf16 v[82:85], v[168:171], v[212:215], v[82:85]
	v_mfma_f32_16x16x32_bf16 v[78:81], v[130:133], v[220:223], v[78:81]
	v_mfma_f32_16x16x32_bf16 v[74:77], v[168:171], v[220:223], v[74:77]
	v_mfma_f32_16x16x32_bf16 v[70:73], v[130:133], v[228:231], v[70:73]
	v_mfma_f32_16x16x32_bf16 v[66:69], v[168:171], v[228:231], v[66:69]
	v_mfma_f32_16x16x32_bf16 v[94:97], v[164:167], v[208:211], v[94:97]
	v_mfma_f32_16x16x32_bf16 v[90:93], v[172:175], v[208:211], v[90:93]
	v_mfma_f32_16x16x32_bf16 v[86:89], v[164:167], v[216:219], v[86:89]
	v_mfma_f32_16x16x32_bf16 v[82:85], v[172:175], v[216:219], v[82:85]
	v_mfma_f32_16x16x32_bf16 v[78:81], v[164:167], v[224:227], v[78:81]
	v_mfma_f32_16x16x32_bf16 v[74:77], v[172:175], v[224:227], v[74:77]
	v_mfma_f32_16x16x32_bf16 v[70:73], v[164:167], v[232:235], v[70:73]
	v_mfma_f32_16x16x32_bf16 v[66:69], v[172:175], v[232:235], v[66:69]
	s_setprio 0
	s_setprio 1
	v_mfma_f32_16x16x32_bf16 v[30:33], v[188:191], v[204:207], v[30:33]
	v_mfma_f32_16x16x32_bf16 v[26:29], v[196:199], v[204:207], v[26:29]
	v_mfma_f32_16x16x32_bf16 v[22:25], v[188:191], v[212:215], v[22:25]
	v_mfma_f32_16x16x32_bf16 v[18:21], v[196:199], v[212:215], v[18:21]
	v_mfma_f32_16x16x32_bf16 v[14:17], v[188:191], v[220:223], v[14:17]
	v_mfma_f32_16x16x32_bf16 v[10:13], v[196:199], v[220:223], v[10:13]
	v_mfma_f32_16x16x32_bf16 v[6:9], v[188:191], v[228:231], v[6:9]
	v_mfma_f32_16x16x32_bf16 v[2:5], v[196:199], v[228:231], v[2:5]
	v_mfma_f32_16x16x32_bf16 v[30:33], v[192:195], v[208:211], v[30:33]
	v_mfma_f32_16x16x32_bf16 v[26:29], v[200:203], v[208:211], v[26:29]
	v_mfma_f32_16x16x32_bf16 v[22:25], v[192:195], v[216:219], v[22:25]
	v_mfma_f32_16x16x32_bf16 v[18:21], v[200:203], v[216:219], v[18:21]
	v_mfma_f32_16x16x32_bf16 v[14:17], v[192:195], v[224:227], v[14:17]
	v_mfma_f32_16x16x32_bf16 v[10:13], v[200:203], v[224:227], v[10:13]
	v_mfma_f32_16x16x32_bf16 v[6:9], v[192:195], v[232:235], v[6:9]
	v_mfma_f32_16x16x32_bf16 v[2:5], v[200:203], v[232:235], v[2:5]
	s_setprio 0
	s_barrier
	s_add_i32 s37, 0, 0x18000
	v_add_u32_e32 v140, s37, v147
	s_add_i32 s38, 0, 0x1c000
	ds_read_b128 v[130:133], v140
	ds_read_b128 v[164:167], v140 offset:1024
	ds_read_b128 v[168:171], v140 offset:2048
	ds_read_b128 v[172:175], v140 offset:3072
	v_add_u32_e32 v140, s38, v147
	ds_read_b128 v[188:191], v140
	ds_read_b128 v[192:195], v140 offset:1024
	ds_read_b128 v[196:199], v140 offset:2048
	ds_read_b128 v[200:203], v140 offset:3072
	s_add_u32 s30, s30, 0x40000
	s_addc_u32 s31, s31, 0
	s_mov_b32 m0, s44
	v_lshl_add_u64 v[242:243], s[30:31], 0, v[136:137]
	ds_read_b128 v[204:207], v180 offset:32768
	ds_read_b128 v[208:211], v180 offset:33792
	ds_read_b128 v[212:215], v180 offset:34816
	ds_read_b128 v[216:219], v180 offset:35840
	ds_read_b128 v[220:223], v180 offset:36864
	ds_read_b128 v[224:227], v180 offset:37888
	ds_read_b128 v[228:231], v180 offset:38912
	ds_read_b128 v[232:235], v180 offset:39936
	global_load_lds_dwordx4 v[242:243], off
	v_lshl_add_u64 v[242:243], s[30:31], 0, v[138:139]
	s_mov_b32 m0, s45
	s_nop 0
	global_load_lds_dwordx4 v[242:243], off
	s_waitcnt vmcnt(8)
	s_waitcnt lgkmcnt(0)
	s_barrier
	s_setprio 1
	v_mfma_f32_16x16x32_bf16 v[126:129], v[130:133], v[204:207], v[126:129]
	v_mfma_f32_16x16x32_bf16 v[122:125], v[168:171], v[204:207], v[122:125]
	v_mfma_f32_16x16x32_bf16 v[118:121], v[130:133], v[212:215], v[118:121]
	v_mfma_f32_16x16x32_bf16 v[114:117], v[168:171], v[212:215], v[114:117]
	v_mfma_f32_16x16x32_bf16 v[110:113], v[130:133], v[220:223], v[110:113]
	v_mfma_f32_16x16x32_bf16 v[106:109], v[168:171], v[220:223], v[106:109]
	v_mfma_f32_16x16x32_bf16 v[102:105], v[130:133], v[228:231], v[102:105]
	v_mfma_f32_16x16x32_bf16 v[98:101], v[168:171], v[228:231], v[98:101]
	v_mfma_f32_16x16x32_bf16 v[126:129], v[164:167], v[208:211], v[126:129]
	v_mfma_f32_16x16x32_bf16 v[122:125], v[172:175], v[208:211], v[122:125]
	v_mfma_f32_16x16x32_bf16 v[118:121], v[164:167], v[216:219], v[118:121]
	v_mfma_f32_16x16x32_bf16 v[114:117], v[172:175], v[216:219], v[114:117]
	v_mfma_f32_16x16x32_bf16 v[110:113], v[164:167], v[224:227], v[110:113]
	v_mfma_f32_16x16x32_bf16 v[106:109], v[172:175], v[224:227], v[106:109]
	v_mfma_f32_16x16x32_bf16 v[102:105], v[164:167], v[232:235], v[102:105]
	v_mfma_f32_16x16x32_bf16 v[98:101], v[172:175], v[232:235], v[98:101]
	s_setprio 0
	s_setprio 1
	v_mfma_f32_16x16x32_bf16 v[62:65], v[188:191], v[204:207], v[62:65]
	v_mfma_f32_16x16x32_bf16 v[58:61], v[196:199], v[204:207], v[58:61]
	v_mfma_f32_16x16x32_bf16 v[54:57], v[188:191], v[212:215], v[54:57]
	v_mfma_f32_16x16x32_bf16 v[50:53], v[196:199], v[212:215], v[50:53]
	v_mfma_f32_16x16x32_bf16 v[46:49], v[188:191], v[220:223], v[46:49]
	v_mfma_f32_16x16x32_bf16 v[42:45], v[196:199], v[220:223], v[42:45]
	v_mfma_f32_16x16x32_bf16 v[38:41], v[188:191], v[228:231], v[38:41]
	v_mfma_f32_16x16x32_bf16 v[34:37], v[196:199], v[228:231], v[34:37]
	v_mfma_f32_16x16x32_bf16 v[62:65], v[192:195], v[208:211], v[62:65]
	v_mfma_f32_16x16x32_bf16 v[58:61], v[200:203], v[208:211], v[58:61]
	v_mfma_f32_16x16x32_bf16 v[54:57], v[192:195], v[216:219], v[54:57]
	v_mfma_f32_16x16x32_bf16 v[50:53], v[200:203], v[216:219], v[50:53]
	v_mfma_f32_16x16x32_bf16 v[46:49], v[192:195], v[224:227], v[46:49]
	v_mfma_f32_16x16x32_bf16 v[42:45], v[200:203], v[224:227], v[42:45]
	v_mfma_f32_16x16x32_bf16 v[38:41], v[192:195], v[232:235], v[38:41]
	v_mfma_f32_16x16x32_bf16 v[34:37], v[200:203], v[232:235], v[34:37]
	s_setprio 0
	s_barrier
; #define PG8_STAGE(bufoff, gbase) do { _Pragma("unroll") for (int _i = 0; _i < 2; ++_i) \
;         __builtin_amdgcn_global_load_lds((const unsigned*)((const char*)(gbase) + voff[_i]), (LAS unsigned*)(lds + (bufoff) + ldsw + _i * 8192), 16, 0, 0); } while (0)
; #define PG8_LDA(dst, b, h) do { _Pragma("unroll") for (int m = 0; m < 4; ++m) _Pragma("unroll") for (int k = 0; k < 2; ++k) dst[m][k] = *(const LAS bf16x8*)(lds + PG8_SA(b, h) + aoff + m * 2048 + k * 1024); } while (0)
; #define PG8_MMA(ai, bj, At, Bt) do { __builtin_amdgcn_s_setprio(1); _Pragma("unroll") for (int m = 0; m < 4; ++m) _Pragma("unroll") for (int n = 0; n < 2; ++n) _Pragma("unroll") for (int k = 0; k < 2; ++k) \
;         acc[ai][bj][m][n] = __builtin_amdgcn_mfma_f32_16x16x32_bf16(Bt[n][k], At[m][k], acc[ai][bj][m][n], 0, 0, 0); __builtin_amdgcn_s_setprio(0); } while (0)
; #define PG8_WAIT_V(n) asm volatile("s_waitcnt vmcnt(" #n ")" ::: "memory")
; #define PG8_WAIT_L(n) asm volatile("s_waitcnt lgkmcnt(" #n ")" ::: "memory")
; #define PG8_BAR __builtin_amdgcn_s_barrier()
; #define PG8_SCHED __builtin_amdgcn_sched_barrier(0)
; template <int EPI> ...
;     ...
;             PG8_LDA(At, 1, 1); PG8_STAGE(PG8_SB(1, 0), b3); PG8_STAGE(PG8_SB(1, 1), b3 + hstep); PG8_STAGE(PG8_SA(1, 0), a3);
;             PG8_WAIT_V(8); PG8_WAIT_L(0); PG8_BAR; PG8_MMA(1, 0, At, B0); PG8_MMA(1, 1, At, B1); PG8_BAR; PG8_SCHED;
;         }
;         if (wr == 0) PG8_BAR;
	s_add_i32 s30, s37, s41
	v_lshl_add_u64 v[176:177], v[176:177], 0, s[10:11]
	s_mov_b32 m0, s30
	ds_read_b128 v[204:207], v180 offset:49152
	ds_read_b128 v[208:211], v180 offset:50176
	ds_read_b128 v[212:215], v180 offset:51200
	ds_read_b128 v[216:219], v180 offset:52224
	ds_read_b128 v[220:223], v180 offset:53248
	ds_read_b128 v[224:227], v180 offset:54272
	ds_read_b128 v[228:231], v180 offset:55296
	ds_read_b128 v[232:235], v180 offset:56320
	global_load_lds_dwordx4 v[176:177], off
	s_add_i32 m0, s30, 0x2000
	s_add_u32 s28, s28, 0x40080
	v_lshl_add_u64 v[176:177], v[236:237], 0, s[10:11]
	s_addc_u32 s29, s29, 0
	s_add_i32 s30, s38, s41
	global_load_lds_dwordx4 v[176:177], off
	v_lshl_add_u64 v[176:177], s[28:29], 0, v[136:137]
	s_mov_b32 m0, s30
	s_nop 0
	global_load_lds_dwordx4 v[176:177], off
	v_lshl_add_u64 v[176:177], s[28:29], 0, v[138:139]
	s_add_i32 m0, s30, 0x2000
	s_nop 0
	global_load_lds_dwordx4 v[176:177], off
	v_lshl_add_u64 v[176:177], v[238:239], 0, s[10:11]
	s_mov_b32 m0, s48
	s_nop 0
	global_load_lds_dwordx4 v[176:177], off
	v_lshl_add_u64 v[176:177], v[240:241], 0, s[10:11]
	s_mov_b32 m0, s49
	s_nop 0
	global_load_lds_dwordx4 v[176:177], off
	s_waitcnt vmcnt(8)
	s_waitcnt lgkmcnt(0)
	s_barrier
	s_setprio 1
	v_mfma_f32_16x16x32_bf16 v[94:97], v[130:133], v[204:207], v[94:97]
	v_mfma_f32_16x16x32_bf16 v[90:93], v[168:171], v[204:207], v[90:93]
	v_mfma_f32_16x16x32_bf16 v[86:89], v[130:133], v[212:215], v[86:89]
	v_mfma_f32_16x16x32_bf16 v[82:85], v[168:171], v[212:215], v[82:85]
	v_mfma_f32_16x16x32_bf16 v[78:81], v[130:133], v[220:223], v[78:81]
	v_mfma_f32_16x16x32_bf16 v[74:77], v[168:171], v[220:223], v[74:77]
	v_mfma_f32_16x16x32_bf16 v[70:73], v[130:133], v[228:231], v[70:73]
	v_mfma_f32_16x16x32_bf16 v[66:69], v[168:171], v[228:231], v[66:69]
	v_mfma_f32_16x16x32_bf16 v[94:97], v[164:167], v[208:211], v[94:97]
	v_mfma_f32_16x16x32_bf16 v[90:93], v[172:175], v[208:211], v[90:93]
	v_mfma_f32_16x16x32_bf16 v[86:89], v[164:167], v[216:219], v[86:89]
	v_mfma_f32_16x16x32_bf16 v[82:85], v[172:175], v[216:219], v[82:85]
	v_mfma_f32_16x16x32_bf16 v[78:81], v[164:167], v[224:227], v[78:81]
	v_mfma_f32_16x16x32_bf16 v[74:77], v[172:175], v[224:227], v[74:77]
	v_mfma_f32_16x16x32_bf16 v[70:73], v[164:167], v[232:235], v[70:73]
	v_mfma_f32_16x16x32_bf16 v[66:69], v[172:175], v[232:235], v[66:69]
	s_setprio 0
	s_setprio 1
	v_mfma_f32_16x16x32_bf16 v[30:33], v[188:191], v[204:207], v[30:33]
	v_mfma_f32_16x16x32_bf16 v[26:29], v[196:199], v[204:207], v[26:29]
	v_mfma_f32_16x16x32_bf16 v[22:25], v[188:191], v[212:215], v[22:25]
	v_mfma_f32_16x16x32_bf16 v[18:21], v[196:199], v[212:215], v[18:21]
	v_mfma_f32_16x16x32_bf16 v[14:17], v[188:191], v[220:223], v[14:17]
	v_mfma_f32_16x16x32_bf16 v[10:13], v[196:199], v[220:223], v[10:13]
	v_mfma_f32_16x16x32_bf16 v[6:9], v[188:191], v[228:231], v[6:9]
	v_mfma_f32_16x16x32_bf16 v[2:5], v[196:199], v[228:231], v[2:5]
	v_mfma_f32_16x16x32_bf16 v[30:33], v[192:195], v[208:211], v[30:33]
	v_mfma_f32_16x16x32_bf16 v[26:29], v[200:203], v[208:211], v[26:29]
	v_mfma_f32_16x16x32_bf16 v[22:25], v[192:195], v[216:219], v[22:25]
	v_mfma_f32_16x16x32_bf16 v[18:21], v[200:203], v[216:219], v[18:21]
	v_mfma_f32_16x16x32_bf16 v[14:17], v[192:195], v[224:227], v[14:17]
	v_mfma_f32_16x16x32_bf16 v[10:13], v[200:203], v[224:227], v[10:13]
	v_mfma_f32_16x16x32_bf16 v[6:9], v[192:195], v[232:235], v[6:9]
	v_mfma_f32_16x16x32_bf16 v[2:5], v[200:203], v[232:235], v[2:5]
	s_setprio 0
	s_barrier
	s_add_i32 s36, s36, 2
	s_add_u32 s26, s26, 0x100
	s_addc_u32 s27, s27, 0
	s_add_u32 s34, s34, 0x100
	s_addc_u32 s35, s35, 0
	s_cmp_gt_u32 s36, 13
	s_cbranch_scc0 .LBB0_137
	s_and_b64 vcc, exec, s[12:13]
	s_cbranch_vccz .LBB0_140
	s_barrier

; #define PG8_STAGE(bufoff, gbase) do { _Pragma("unroll") for (int _i = 0; _i < 2; ++_i) \
;         __builtin_amdgcn_global_load_lds((const unsigned*)((const char*)(gbase) + voff[_i]), (LAS unsigned*)(lds + (bufoff) + ldsw + _i * 8192), 16, 0, 0); } while (0)
; #define PG8_LDA(dst, b, h) do { _Pragma("unroll") for (int m = 0; m < 4; ++m) _Pragma("unroll") for (int k = 0; k < 2; ++k) dst[m][k] = *(const LAS bf16x8*)(lds + PG8_SA(b, h) + aoff + m * 2048 + k * 1024); } while (0)
; #define PG8_LDB(dst, b, h) do { _Pragma("unroll") for (int n = 0; n < 2; ++n) _Pragma("unroll") for (int k = 0; k < 2; ++k) dst[n][k] = *(const LAS bf16x8*)(lds + PG8_SB(b, h) + boff + n * 2048 + k * 1024); } while (0)
; #define PG8_MMA(ai, bj, At, Bt) do { __builtin_amdgcn_s_setprio(1); _Pragma("unroll") for (int m = 0; m < 4; ++m) _Pragma("unroll") for (int n = 0; n < 2; ++n) _Pragma("unroll") for (int k = 0; k < 2; ++k) \
;         acc[ai][bj][m][n] = __builtin_amdgcn_mfma_f32_16x16x32_bf16(Bt[n][k], At[m][k], acc[ai][bj][m][n], 0, 0, 0); __builtin_amdgcn_s_setprio(0); } while (0)
; #define PG8_WAIT_V(n) asm volatile("s_waitcnt vmcnt(" #n ")" ::: "memory")
; #define PG8_WAIT_L(n) asm volatile("s_waitcnt lgkmcnt(" #n ")" ::: "memory")
; #define PG8_BAR __builtin_amdgcn_s_barrier()
; #define PG8_SCHED __builtin_amdgcn_sched_barrier(0)
; template <int EPI> ...
;     ...
;         for (int t = 0; t < cnk; t += 2) {
;             const bool last = (t == cnk - 2);
;             const char* a1 = cA + (size_t)(t + 1) * kstep;
;             const char* a2 = last ? nA : cA + (size_t)(t + 2) * kstep; const char* b2 = last ? nB : cB + (size_t)(t + 2) * kstep;
;             const char* a3 = a2 + kstep; const char* b3 = b2 + kstep;
;             PG8_LDB(B0, 0, 0); PG8_LDB(B1, 0, 1); PG8_SCHED; PG8_LDA(At, 0, 0); PG8_STAGE(PG8_SA(1, 1), a1 + hstep);
;             PG8_WAIT_V(8); PG8_WAIT_L(0); PG8_BAR; PG8_MMA(0, 0, At, B0); PG8_MMA(0, 1, At, B1); PG8_BAR; PG8_SCHED;
;             PG8_LDA(At, 0, 1); PG8_STAGE(PG8_SB(0, 0), b2); PG8_STAGE(PG8_SB(0, 1), b2 + hstep); PG8_STAGE(PG8_SA(0, 0), a2);
;             PG8_WAIT_V(8); PG8_WAIT_L(0); PG8_BAR; PG8_MMA(1, 0, At, B0); PG8_MMA(1, 1, At, B1); PG8_BAR; PG8_SCHED;
.LBB0_656:
	ds_read_b128 v[142:145], v158
	ds_read_b128 v[146:149], v158 offset:1024
	ds_read_b128 v[162:165], v158 offset:2048
	ds_read_b128 v[166:169], v158 offset:3072
	ds_read_b128 v[170:173], v159
	ds_read_b128 v[174:177], v159 offset:1024
	ds_read_b128 v[178:181], v159 offset:2048
	ds_read_b128 v[188:191], v159 offset:3072
	s_add_i32 s63, s62, 2
	s_add_u32 s28, s26, 0xfffe0080
	s_addc_u32 s29, s27, -1
	s_cmp_eq_u32 s59, s62
	s_cselect_b32 s31, s5, s29
	s_cselect_b32 s30, s19, s28
	s_cselect_b32 s29, s17, s61
	s_cselect_b32 s28, s58, s60
	v_lshl_add_u64 v[224:225], s[26:27], 0, v[136:137]
	s_add_i32 m0, s7, 0xc000
	ds_read_b128 v[192:195], v160
	ds_read_b128 v[196:199], v160 offset:1024
	ds_read_b128 v[200:203], v160 offset:2048
	ds_read_b128 v[204:207], v160 offset:3072
	ds_read_b128 v[208:211], v160 offset:4096
	ds_read_b128 v[212:215], v160 offset:5120
	ds_read_b128 v[216:219], v160 offset:6144
	ds_read_b128 v[220:223], v160 offset:7168
	global_load_lds_dwordx4 v[224:225], off
	v_lshl_add_u64 v[224:225], s[26:27], 0, v[138:139]
	s_add_i32 m0, s7, 0xe000
	s_nop 0
	global_load_lds_dwordx4 v[224:225], off
	s_waitcnt vmcnt(8)
	s_waitcnt lgkmcnt(0)
	s_barrier
	s_setprio 1
	v_mfma_f32_16x16x32_bf16 v[126:129], v[142:145], v[192:195], v[126:129]
	v_mfma_f32_16x16x32_bf16 v[122:125], v[162:165], v[192:195], v[122:125]
	v_mfma_f32_16x16x32_bf16 v[118:121], v[142:145], v[200:203], v[118:121]
	v_mfma_f32_16x16x32_bf16 v[114:117], v[162:165], v[200:203], v[114:117]
	v_mfma_f32_16x16x32_bf16 v[106:109], v[142:145], v[208:211], v[106:109]
	v_mfma_f32_16x16x32_bf16 v[98:101], v[162:165], v[208:211], v[98:101]
	v_mfma_f32_16x16x32_bf16 v[90:93], v[142:145], v[216:219], v[90:93]
	v_mfma_f32_16x16x32_bf16 v[82:85], v[162:165], v[216:219], v[82:85]
	v_mfma_f32_16x16x32_bf16 v[126:129], v[146:149], v[196:199], v[126:129]
	v_mfma_f32_16x16x32_bf16 v[122:125], v[166:169], v[196:199], v[122:125]
	v_mfma_f32_16x16x32_bf16 v[118:121], v[146:149], v[204:207], v[118:121]
	v_mfma_f32_16x16x32_bf16 v[114:117], v[166:169], v[204:207], v[114:117]
	v_mfma_f32_16x16x32_bf16 v[106:109], v[146:149], v[212:215], v[106:109]
	v_mfma_f32_16x16x32_bf16 v[98:101], v[166:169], v[212:215], v[98:101]
	v_mfma_f32_16x16x32_bf16 v[90:93], v[146:149], v[220:223], v[90:93]
	v_mfma_f32_16x16x32_bf16 v[82:85], v[166:169], v[220:223], v[82:85]
	s_setprio 0
	s_setprio 1
	v_mfma_f32_16x16x32_bf16 v[110:113], v[170:173], v[192:195], v[110:113]
	v_mfma_f32_16x16x32_bf16 v[102:105], v[178:181], v[192:195], v[102:105]
	v_mfma_f32_16x16x32_bf16 v[94:97], v[170:173], v[200:203], v[94:97]
	v_mfma_f32_16x16x32_bf16 v[86:89], v[178:181], v[200:203], v[86:89]
	v_mfma_f32_16x16x32_bf16 v[78:81], v[170:173], v[208:211], v[78:81]
	v_mfma_f32_16x16x32_bf16 v[74:77], v[178:181], v[208:211], v[74:77]
	v_mfma_f32_16x16x32_bf16 v[70:73], v[170:173], v[216:219], v[70:73]
	v_mfma_f32_16x16x32_bf16 v[66:69], v[178:181], v[216:219], v[66:69]
	v_mfma_f32_16x16x32_bf16 v[110:113], v[174:177], v[196:199], v[110:113]
	v_mfma_f32_16x16x32_bf16 v[102:105], v[188:191], v[196:199], v[102:105]
	v_mfma_f32_16x16x32_bf16 v[94:97], v[174:177], v[204:207], v[94:97]
	v_mfma_f32_16x16x32_bf16 v[86:89], v[188:191], v[204:207], v[86:89]
	v_mfma_f32_16x16x32_bf16 v[78:81], v[174:177], v[212:215], v[78:81]
	v_mfma_f32_16x16x32_bf16 v[74:77], v[188:191], v[212:215], v[74:77]
	v_mfma_f32_16x16x32_bf16 v[70:73], v[174:177], v[220:223], v[70:73]
	v_mfma_f32_16x16x32_bf16 v[66:69], v[188:191], v[220:223], v[66:69]
	s_setprio 0
	s_barrier
	s_add_i32 s62, s48, s40
	v_lshl_add_u64 v[224:225], s[28:29], 0, v[130:131]
	s_mov_b32 m0, s62
	ds_read_b128 v[192:195], v160 offset:16384
	ds_read_b128 v[196:199], v160 offset:17408
	ds_read_b128 v[200:203], v160 offset:18432
	ds_read_b128 v[204:207], v160 offset:19456
	ds_read_b128 v[208:211], v160 offset:20480
	ds_read_b128 v[212:215], v160 offset:21504
	ds_read_b128 v[216:219], v160 offset:22528
	ds_read_b128 v[220:223], v160 offset:23552
	global_load_lds_dwordx4 v[224:225], off
	s_add_i32 m0, s62, 0x2000
	s_add_u32 s64, s28, 0x20000
	v_lshl_add_u64 v[226:227], s[28:29], 0, v[132:133]
	s_addc_u32 s65, s29, 0
	s_add_i32 s62, s49, s40
	global_load_lds_dwordx4 v[226:227], off
	v_lshl_add_u64 v[228:229], s[64:65], 0, v[130:131]
	s_mov_b32 m0, s62
	v_lshl_add_u64 v[230:231], s[30:31], 0, v[132:133]
	global_load_lds_dwordx4 v[228:229], off
	v_lshl_add_u64 v[228:229], s[64:65], 0, v[132:133]
	s_add_i32 m0, s62, 0x2000
	s_nop 0
	global_load_lds_dwordx4 v[228:229], off
	v_lshl_add_u64 v[228:229], s[30:31], 0, v[130:131]
	s_mov_b32 m0, s7
	s_nop 0
	global_load_lds_dwordx4 v[228:229], off
	s_mov_b32 m0, s42
	s_nop 0
	global_load_lds_dwordx4 v[230:231], off
	s_waitcnt vmcnt(8)
	s_waitcnt lgkmcnt(0)
	s_barrier
; #define PG8_STAGE(bufoff, gbase) do { _Pragma("unroll") for (int _i = 0; _i < 2; ++_i) \
;         __builtin_amdgcn_global_load_lds((const unsigned*)((const char*)(gbase) + voff[_i]), (LAS unsigned*)(lds + (bufoff) + ldsw + _i * 8192), 16, 0, 0); } while (0)
; #define PG8_LDA(dst, b, h) do { _Pragma("unroll") for (int m = 0; m < 4; ++m) _Pragma("unroll") for (int k = 0; k < 2; ++k) dst[m][k] = *(const LAS bf16x8*)(lds + PG8_SA(b, h) + aoff + m * 2048 + k * 1024); } while (0)
; #define PG8_LDB(dst, b, h) do { _Pragma("unroll") for (int n = 0; n < 2; ++n) _Pragma("unroll") for (int k = 0; k < 2; ++k) dst[n][k] = *(const LAS bf16x8*)(lds + PG8_SB(b, h) + boff + n * 2048 + k * 1024); } while (0)
; #define PG8_MMA(ai, bj, At, Bt) do { __builtin_amdgcn_s_setprio(1); _Pragma("unroll") for (int m = 0; m < 4; ++m) _Pragma("unroll") for (int n = 0; n < 2; ++n) _Pragma("unroll") for (int k = 0; k < 2; ++k) \
;         acc[ai][bj][m][n] = __builtin_amdgcn_mfma_f32_16x16x32_bf16(Bt[n][k], At[m][k], acc[ai][bj][m][n], 0, 0, 0); __builtin_amdgcn_s_setprio(0); } while (0)
; #define PG8_WAIT_V(n) asm volatile("s_waitcnt vmcnt(" #n ")" ::: "memory")
; #define PG8_WAIT_L(n) asm volatile("s_waitcnt lgkmcnt(" #n ")" ::: "memory")
; #define PG8_BAR __builtin_amdgcn_s_barrier()
; #define PG8_SCHED __builtin_amdgcn_sched_barrier(0)
; template <int EPI> ...
;     ...
;             PG8_WAIT_V(8); PG8_WAIT_L(0); PG8_BAR; PG8_MMA(1, 0, At, B0); PG8_MMA(1, 1, At, B1); PG8_BAR; PG8_SCHED;
;             PG8_LDB(B0, 1, 0); PG8_LDB(B1, 1, 1); PG8_SCHED; PG8_LDA(At, 1, 0); PG8_STAGE(PG8_SA(0, 1), a2 + hstep);
;             PG8_WAIT_V(8); PG8_WAIT_L(0); PG8_BAR; PG8_MMA(0, 0, At, B0); PG8_MMA(0, 1, At, B1); PG8_BAR; PG8_SCHED;
	s_setprio 1
	v_mfma_f32_16x16x32_bf16 v[62:65], v[142:145], v[192:195], v[62:65]
	v_mfma_f32_16x16x32_bf16 v[58:61], v[162:165], v[192:195], v[58:61]
	v_mfma_f32_16x16x32_bf16 v[54:57], v[142:145], v[200:203], v[54:57]
	v_mfma_f32_16x16x32_bf16 v[50:53], v[162:165], v[200:203], v[50:53]
	v_mfma_f32_16x16x32_bf16 v[42:45], v[142:145], v[208:211], v[42:45]
	v_mfma_f32_16x16x32_bf16 v[34:37], v[162:165], v[208:211], v[34:37]
	v_mfma_f32_16x16x32_bf16 v[26:29], v[142:145], v[216:219], v[26:29]
	v_mfma_f32_16x16x32_bf16 v[18:21], v[162:165], v[216:219], v[18:21]
	v_mfma_f32_16x16x32_bf16 v[62:65], v[146:149], v[196:199], v[62:65]
	v_mfma_f32_16x16x32_bf16 v[58:61], v[166:169], v[196:199], v[58:61]
	v_mfma_f32_16x16x32_bf16 v[54:57], v[146:149], v[204:207], v[54:57]
	v_mfma_f32_16x16x32_bf16 v[50:53], v[166:169], v[204:207], v[50:53]
	v_mfma_f32_16x16x32_bf16 v[42:45], v[146:149], v[212:215], v[42:45]
	v_mfma_f32_16x16x32_bf16 v[34:37], v[166:169], v[212:215], v[34:37]
	v_mfma_f32_16x16x32_bf16 v[26:29], v[146:149], v[220:223], v[26:29]
	v_mfma_f32_16x16x32_bf16 v[18:21], v[166:169], v[220:223], v[18:21]
	s_setprio 0
	s_setprio 1
	v_mfma_f32_16x16x32_bf16 v[46:49], v[170:173], v[192:195], v[46:49]
	v_mfma_f32_16x16x32_bf16 v[38:41], v[178:181], v[192:195], v[38:41]
	v_mfma_f32_16x16x32_bf16 v[30:33], v[170:173], v[200:203], v[30:33]
	v_mfma_f32_16x16x32_bf16 v[22:25], v[178:181], v[200:203], v[22:25]
	v_mfma_f32_16x16x32_bf16 v[14:17], v[170:173], v[208:211], v[14:17]
	v_mfma_f32_16x16x32_bf16 v[10:13], v[178:181], v[208:211], v[10:13]
	v_mfma_f32_16x16x32_bf16 v[6:9], v[170:173], v[216:219], v[6:9]
	v_mfma_f32_16x16x32_bf16 v[2:5], v[178:181], v[216:219], v[2:5]
	v_mfma_f32_16x16x32_bf16 v[46:49], v[174:177], v[196:199], v[46:49]
	v_mfma_f32_16x16x32_bf16 v[38:41], v[188:191], v[196:199], v[38:41]
	v_mfma_f32_16x16x32_bf16 v[30:33], v[174:177], v[204:207], v[30:33]
	v_mfma_f32_16x16x32_bf16 v[22:25], v[188:191], v[204:207], v[22:25]
	v_mfma_f32_16x16x32_bf16 v[14:17], v[174:177], v[212:215], v[14:17]
	v_mfma_f32_16x16x32_bf16 v[10:13], v[188:191], v[212:215], v[10:13]
	v_mfma_f32_16x16x32_bf16 v[6:9], v[174:177], v[220:223], v[6:9]
	v_mfma_f32_16x16x32_bf16 v[2:5], v[188:191], v[220:223], v[2:5]
	s_setprio 0
	s_barrier
	s_add_i32 s62, 0, 0x18000
	v_add_u32_e32 v134, s62, v152
	s_add_i32 s64, 0, 0x1c000
	ds_read_b128 v[142:145], v134
	ds_read_b128 v[146:149], v134 offset:1024
	ds_read_b128 v[162:165], v134 offset:2048
	ds_read_b128 v[166:169], v134 offset:3072
	v_add_u32_e32 v134, s64, v152
	ds_read_b128 v[170:173], v134
	ds_read_b128 v[174:177], v134 offset:1024
	ds_read_b128 v[178:181], v134 offset:2048
	ds_read_b128 v[188:191], v134 offset:3072
	s_add_u32 s30, s30, 0x20000
	s_addc_u32 s31, s31, 0
	s_mov_b32 m0, s43
	v_lshl_add_u64 v[232:233], s[30:31], 0, v[130:131]
	ds_read_b128 v[192:195], v160 offset:32768
	ds_read_b128 v[196:199], v160 offset:33792
	ds_read_b128 v[200:203], v160 offset:34816
	ds_read_b128 v[204:207], v160 offset:35840
	ds_read_b128 v[208:211], v160 offset:36864
	ds_read_b128 v[212:215], v160 offset:37888
	ds_read_b128 v[216:219], v160 offset:38912
	ds_read_b128 v[220:223], v160 offset:39936
	global_load_lds_dwordx4 v[232:233], off
	v_lshl_add_u64 v[232:233], s[30:31], 0, v[132:133]
	s_mov_b32 m0, s44
	s_nop 0
	global_load_lds_dwordx4 v[232:233], off
	s_waitcnt vmcnt(8)
	s_waitcnt lgkmcnt(0)
	s_barrier
	s_setprio 1
	v_mfma_f32_16x16x32_bf16 v[126:129], v[142:145], v[192:195], v[126:129]
	v_mfma_f32_16x16x32_bf16 v[122:125], v[162:165], v[192:195], v[122:125]
	v_mfma_f32_16x16x32_bf16 v[118:121], v[142:145], v[200:203], v[118:121]
	v_mfma_f32_16x16x32_bf16 v[114:117], v[162:165], v[200:203], v[114:117]
	v_mfma_f32_16x16x32_bf16 v[106:109], v[142:145], v[208:211], v[106:109]
	v_mfma_f32_16x16x32_bf16 v[98:101], v[162:165], v[208:211], v[98:101]
	v_mfma_f32_16x16x32_bf16 v[90:93], v[142:145], v[216:219], v[90:93]
	v_mfma_f32_16x16x32_bf16 v[82:85], v[162:165], v[216:219], v[82:85]
	v_mfma_f32_16x16x32_bf16 v[126:129], v[146:149], v[196:199], v[126:129]
	v_mfma_f32_16x16x32_bf16 v[122:125], v[166:169], v[196:199], v[122:125]
	v_mfma_f32_16x16x32_bf16 v[118:121], v[146:149], v[204:207], v[118:121]
	v_mfma_f32_16x16x32_bf16 v[114:117], v[166:169], v[204:207], v[114:117]
	v_mfma_f32_16x16x32_bf16 v[106:109], v[146:149], v[212:215], v[106:109]
	v_mfma_f32_16x16x32_bf16 v[98:101], v[166:169], v[212:215], v[98:101]
	v_mfma_f32_16x16x32_bf16 v[90:93], v[146:149], v[220:223], v[90:93]
	v_mfma_f32_16x16x32_bf16 v[82:85], v[166:169], v[220:223], v[82:85]
	s_setprio 0
	s_setprio 1
	v_mfma_f32_16x16x32_bf16 v[110:113], v[170:173], v[192:195], v[110:113]
	v_mfma_f32_16x16x32_bf16 v[102:105], v[178:181], v[192:195], v[102:105]
	v_mfma_f32_16x16x32_bf16 v[94:97], v[170:173], v[200:203], v[94:97]
	v_mfma_f32_16x16x32_bf16 v[86:89], v[178:181], v[200:203], v[86:89]
	v_mfma_f32_16x16x32_bf16 v[78:81], v[170:173], v[208:211], v[78:81]
	v_mfma_f32_16x16x32_bf16 v[74:77], v[178:181], v[208:211], v[74:77]
	v_mfma_f32_16x16x32_bf16 v[70:73], v[170:173], v[216:219], v[70:73]
	v_mfma_f32_16x16x32_bf16 v[66:69], v[178:181], v[216:219], v[66:69]
	v_mfma_f32_16x16x32_bf16 v[110:113], v[174:177], v[196:199], v[110:113]
	v_mfma_f32_16x16x32_bf16 v[102:105], v[188:191], v[196:199], v[102:105]
	v_mfma_f32_16x16x32_bf16 v[94:97], v[174:177], v[204:207], v[94:97]
	v_mfma_f32_16x16x32_bf16 v[86:89], v[188:191], v[204:207], v[86:89]
	v_mfma_f32_16x16x32_bf16 v[78:81], v[174:177], v[212:215], v[78:81]
	v_mfma_f32_16x16x32_bf16 v[74:77], v[188:191], v[212:215], v[74:77]
	v_mfma_f32_16x16x32_bf16 v[70:73], v[174:177], v[220:223], v[70:73]
	v_mfma_f32_16x16x32_bf16 v[66:69], v[188:191], v[220:223], v[66:69]
	s_setprio 0
	s_barrier
; #define PG8_STAGE(bufoff, gbase) do { _Pragma("unroll") for (int _i = 0; _i < 2; ++_i) \
;         __builtin_amdgcn_global_load_lds((const unsigned*)((const char*)(gbase) + voff[_i]), (LAS unsigned*)(lds + (bufoff) + ldsw + _i * 8192), 16, 0, 0); } while (0)
; #define PG8_LDA(dst, b, h) do { _Pragma("unroll") for (int m = 0; m < 4; ++m) _Pragma("unroll") for (int k = 0; k < 2; ++k) dst[m][k] = *(const LAS bf16x8*)(lds + PG8_SA(b, h) + aoff + m * 2048 + k * 1024); } while (0)
; #define PG8_MMA(ai, bj, At, Bt) do { __builtin_amdgcn_s_setprio(1); _Pragma("unroll") for (int m = 0; m < 4; ++m) _Pragma("unroll") for (int n = 0; n < 2; ++n) _Pragma("unroll") for (int k = 0; k < 2; ++k) \
;         acc[ai][bj][m][n] = __builtin_amdgcn_mfma_f32_16x16x32_bf16(Bt[n][k], At[m][k], acc[ai][bj][m][n], 0, 0, 0); __builtin_amdgcn_s_setprio(0); } while (0)
; #define PG8_WAIT_V(n) asm volatile("s_waitcnt vmcnt(" #n ")" ::: "memory")
; #define PG8_WAIT_L(n) asm volatile("s_waitcnt lgkmcnt(" #n ")" ::: "memory")
; #define PG8_BAR __builtin_amdgcn_s_barrier()
; #define PG8_SCHED __builtin_amdgcn_sched_barrier(0)
; template <int EPI> ...
;     ...
;             PG8_LDA(At, 1, 1); PG8_STAGE(PG8_SB(1, 0), b3); PG8_STAGE(PG8_SB(1, 1), b3 + hstep); PG8_STAGE(PG8_SA(1, 0), a3);
;             PG8_WAIT_V(8); PG8_WAIT_L(0); PG8_BAR; PG8_MMA(1, 0, At, B0); PG8_MMA(1, 1, At, B1); PG8_BAR; PG8_SCHED;
;         }
;         if (wr == 0) PG8_BAR;
;         if (SPLIT && cur_slice >= 0) {
	s_add_i32 s30, s62, s40
	v_lshl_add_u64 v[224:225], v[224:225], 0, s[10:11]
	s_mov_b32 m0, s30
	ds_read_b128 v[192:195], v160 offset:49152
	ds_read_b128 v[196:199], v160 offset:50176
	ds_read_b128 v[200:203], v160 offset:51200
	ds_read_b128 v[204:207], v160 offset:52224
	ds_read_b128 v[208:211], v160 offset:53248
	ds_read_b128 v[212:215], v160 offset:54272
	ds_read_b128 v[216:219], v160 offset:55296
	ds_read_b128 v[220:223], v160 offset:56320
	global_load_lds_dwordx4 v[224:225], off
	s_add_i32 m0, s30, 0x2000
	s_add_u32 s28, s28, 0x20080
	v_lshl_add_u64 v[224:225], v[226:227], 0, s[10:11]
	s_addc_u32 s29, s29, 0
	s_add_i32 s30, s64, s40
	global_load_lds_dwordx4 v[224:225], off
	v_lshl_add_u64 v[224:225], s[28:29], 0, v[130:131]
	s_mov_b32 m0, s30
	s_nop 0
	global_load_lds_dwordx4 v[224:225], off
	v_lshl_add_u64 v[224:225], s[28:29], 0, v[132:133]
	s_add_i32 m0, s30, 0x2000
	s_nop 0
	global_load_lds_dwordx4 v[224:225], off
	v_lshl_add_u64 v[224:225], v[228:229], 0, s[10:11]
	s_mov_b32 m0, s45
	s_nop 0
	global_load_lds_dwordx4 v[224:225], off
	v_lshl_add_u64 v[224:225], v[230:231], 0, s[10:11]
	s_mov_b32 m0, s46
	s_nop 0
	global_load_lds_dwordx4 v[224:225], off
	s_waitcnt vmcnt(8)
	s_waitcnt lgkmcnt(0)
	s_barrier
	s_setprio 1
	v_mfma_f32_16x16x32_bf16 v[62:65], v[142:145], v[192:195], v[62:65]
	v_mfma_f32_16x16x32_bf16 v[58:61], v[162:165], v[192:195], v[58:61]
	v_mfma_f32_16x16x32_bf16 v[54:57], v[142:145], v[200:203], v[54:57]
	v_mfma_f32_16x16x32_bf16 v[50:53], v[162:165], v[200:203], v[50:53]
	v_mfma_f32_16x16x32_bf16 v[42:45], v[142:145], v[208:211], v[42:45]
	v_mfma_f32_16x16x32_bf16 v[34:37], v[162:165], v[208:211], v[34:37]
	v_mfma_f32_16x16x32_bf16 v[26:29], v[142:145], v[216:219], v[26:29]
	v_mfma_f32_16x16x32_bf16 v[18:21], v[162:165], v[216:219], v[18:21]
	v_mfma_f32_16x16x32_bf16 v[62:65], v[146:149], v[196:199], v[62:65]
	v_mfma_f32_16x16x32_bf16 v[58:61], v[166:169], v[196:199], v[58:61]
	v_mfma_f32_16x16x32_bf16 v[54:57], v[146:149], v[204:207], v[54:57]
	v_mfma_f32_16x16x32_bf16 v[50:53], v[166:169], v[204:207], v[50:53]
	v_mfma_f32_16x16x32_bf16 v[42:45], v[146:149], v[212:215], v[42:45]
	v_mfma_f32_16x16x32_bf16 v[34:37], v[166:169], v[212:215], v[34:37]
	v_mfma_f32_16x16x32_bf16 v[26:29], v[146:149], v[220:223], v[26:29]
	v_mfma_f32_16x16x32_bf16 v[18:21], v[166:169], v[220:223], v[18:21]
	s_setprio 0
	s_setprio 1
	v_mfma_f32_16x16x32_bf16 v[46:49], v[170:173], v[192:195], v[46:49]
	v_mfma_f32_16x16x32_bf16 v[38:41], v[178:181], v[192:195], v[38:41]
	v_mfma_f32_16x16x32_bf16 v[30:33], v[170:173], v[200:203], v[30:33]
	v_mfma_f32_16x16x32_bf16 v[22:25], v[178:181], v[200:203], v[22:25]
	v_mfma_f32_16x16x32_bf16 v[14:17], v[170:173], v[208:211], v[14:17]
	v_mfma_f32_16x16x32_bf16 v[10:13], v[178:181], v[208:211], v[10:13]
	v_mfma_f32_16x16x32_bf16 v[6:9], v[170:173], v[216:219], v[6:9]
	v_mfma_f32_16x16x32_bf16 v[2:5], v[178:181], v[216:219], v[2:5]
	v_mfma_f32_16x16x32_bf16 v[46:49], v[174:177], v[196:199], v[46:49]
	v_mfma_f32_16x16x32_bf16 v[38:41], v[188:191], v[196:199], v[38:41]
	v_mfma_f32_16x16x32_bf16 v[30:33], v[174:177], v[204:207], v[30:33]
	v_mfma_f32_16x16x32_bf16 v[22:25], v[188:191], v[204:207], v[22:25]
	v_mfma_f32_16x16x32_bf16 v[14:17], v[174:177], v[212:215], v[14:17]
	v_mfma_f32_16x16x32_bf16 v[10:13], v[188:191], v[212:215], v[10:13]
	v_mfma_f32_16x16x32_bf16 v[6:9], v[174:177], v[220:223], v[6:9]
	v_mfma_f32_16x16x32_bf16 v[2:5], v[188:191], v[220:223], v[2:5]
	s_setprio 0
	s_barrier
	s_add_u32 s26, s26, 0x100
	s_addc_u32 s27, s27, 0
	s_add_u32 s60, s60, 0x100
	s_addc_u32 s61, s61, 0
	s_cmp_ge_u32 s63, s57
	s_mov_b32 s62, s63
	s_cbranch_scc0 .LBB0_656
	s_and_b64 vcc, exec, s[12:13]
	s_cbranch_vccz .LBB0_661
	s_barrier
	s_cmp_lt_i32 s0, 0
	s_mov_b64 s[26:27], -1
	s_cbranch_scc1 .LBB0_662

; #define PG8_STAGE(bufoff, gbase) do { _Pragma("unroll") for (int _i = 0; _i < 2; ++_i) \
;         __builtin_amdgcn_global_load_lds((const unsigned*)((const char*)(gbase) + voff[_i]), (LAS unsigned*)(lds + (bufoff) + ldsw + _i * 8192), 16, 0, 0); } while (0)
; #define PG8_LDA(dst, b, h) do { _Pragma("unroll") for (int m = 0; m < 4; ++m) _Pragma("unroll") for (int k = 0; k < 2; ++k) dst[m][k] = *(const LAS bf16x8*)(lds + PG8_SA(b, h) + aoff + m * 2048 + k * 1024); } while (0)
; #define PG8_LDB(dst, b, h) do { _Pragma("unroll") for (int n = 0; n < 2; ++n) _Pragma("unroll") for (int k = 0; k < 2; ++k) dst[n][k] = *(const LAS bf16x8*)(lds + PG8_SB(b, h) + boff + n * 2048 + k * 1024); } while (0)
; #define PG8_MMA(ai, bj, At, Bt) do { __builtin_amdgcn_s_setprio(1); _Pragma("unroll") for (int m = 0; m < 4; ++m) _Pragma("unroll") for (int n = 0; n < 2; ++n) _Pragma("unroll") for (int k = 0; k < 2; ++k) \
;         acc[ai][bj][m][n] = __builtin_amdgcn_mfma_f32_16x16x32_bf16(Bt[n][k], At[m][k], acc[ai][bj][m][n], 0, 0, 0); __builtin_amdgcn_s_setprio(0); } while (0)
; #define PG8_WAIT_V(n) asm volatile("s_waitcnt vmcnt(" #n ")" ::: "memory")
; #define PG8_WAIT_L(n) asm volatile("s_waitcnt lgkmcnt(" #n ")" ::: "memory")
; #define PG8_BAR __builtin_amdgcn_s_barrier()
; #define PG8_SCHED __builtin_amdgcn_sched_barrier(0)
; template <int EPI> ...
;     ...
;         for (int t = 0; t < cnk; t += 2) {
;             const bool last = (t == cnk - 2);
;             const char* a1 = cA + (size_t)(t + 1) * kstep;
;             const char* a2 = last ? nA : cA + (size_t)(t + 2) * kstep; const char* b2 = last ? nB : cB + (size_t)(t + 2) * kstep;
;             const char* a3 = a2 + kstep; const char* b3 = b2 + kstep;
;             PG8_LDB(B0, 0, 0); PG8_LDB(B1, 0, 1); PG8_SCHED; PG8_LDA(At, 0, 0); PG8_STAGE(PG8_SA(1, 1), a1 + hstep);
;             PG8_WAIT_V(8); PG8_WAIT_L(0); PG8_BAR; PG8_MMA(0, 0, At, B0); PG8_MMA(0, 1, At, B1); PG8_BAR; PG8_SCHED;
;             PG8_LDA(At, 0, 1); PG8_STAGE(PG8_SB(0, 0), b2); PG8_STAGE(PG8_SB(0, 1), b2 + hstep); PG8_STAGE(PG8_SA(0, 0), a2);
;             PG8_WAIT_V(8); PG8_WAIT_L(0); PG8_BAR; PG8_MMA(1, 0, At, B0); PG8_MMA(1, 1, At, B1); PG8_BAR; PG8_SCHED;
.LBB0_737:
	ds_read_b128 v[142:145], v153
	ds_read_b128 v[146:149], v153 offset:1024
	ds_read_b128 v[156:159], v153 offset:2048
	ds_read_b128 v[160:163], v153 offset:3072
	ds_read_b128 v[164:167], v154
	ds_read_b128 v[168:171], v154 offset:1024
	ds_read_b128 v[172:175], v154 offset:2048
	ds_read_b128 v[176:179], v154 offset:3072
	s_add_u32 s26, s24, 0xfffe0080
	s_addc_u32 s27, s25, -1
	s_cmp_eq_u32 s52, 4
	s_cselect_b32 s29, s17, s27
	s_cselect_b32 s28, s48, s26
	s_cselect_b32 s27, s15, s51
	s_cselect_b32 s26, s49, s50
	v_lshl_add_u64 v[180:181], s[24:25], 0, v[134:135]
	s_add_i32 m0, s23, 0xc000
	ds_read_b128 v[188:191], v155
	ds_read_b128 v[192:195], v155 offset:1024
	ds_read_b128 v[196:199], v155 offset:2048
	ds_read_b128 v[200:203], v155 offset:3072
	ds_read_b128 v[204:207], v155 offset:4096
	ds_read_b128 v[208:211], v155 offset:5120
	ds_read_b128 v[212:215], v155 offset:6144
	ds_read_b128 v[216:219], v155 offset:7168
	global_load_lds_dwordx4 v[180:181], off
	v_lshl_add_u64 v[180:181], s[24:25], 0, v[136:137]
	s_add_i32 m0, s23, 0xe000
	s_nop 0
	global_load_lds_dwordx4 v[180:181], off
	s_waitcnt vmcnt(8)
	s_waitcnt lgkmcnt(0)
	s_barrier
	s_setprio 1
	v_mfma_f32_16x16x32_bf16 v[126:129], v[142:145], v[188:191], v[126:129]
	v_mfma_f32_16x16x32_bf16 v[122:125], v[156:159], v[188:191], v[122:125]
	v_mfma_f32_16x16x32_bf16 v[110:113], v[142:145], v[196:199], v[110:113]
	v_mfma_f32_16x16x32_bf16 v[106:109], v[156:159], v[196:199], v[106:109]
	v_mfma_f32_16x16x32_bf16 v[94:97], v[142:145], v[204:207], v[94:97]
	v_mfma_f32_16x16x32_bf16 v[90:93], v[156:159], v[204:207], v[90:93]
	v_mfma_f32_16x16x32_bf16 v[78:81], v[142:145], v[212:215], v[78:81]
	v_mfma_f32_16x16x32_bf16 v[74:77], v[156:159], v[212:215], v[74:77]
	v_mfma_f32_16x16x32_bf16 v[126:129], v[146:149], v[192:195], v[126:129]
	v_mfma_f32_16x16x32_bf16 v[122:125], v[160:163], v[192:195], v[122:125]
	v_mfma_f32_16x16x32_bf16 v[110:113], v[146:149], v[200:203], v[110:113]
	v_mfma_f32_16x16x32_bf16 v[106:109], v[160:163], v[200:203], v[106:109]
	v_mfma_f32_16x16x32_bf16 v[94:97], v[146:149], v[208:211], v[94:97]
	v_mfma_f32_16x16x32_bf16 v[90:93], v[160:163], v[208:211], v[90:93]
	v_mfma_f32_16x16x32_bf16 v[78:81], v[146:149], v[216:219], v[78:81]
	v_mfma_f32_16x16x32_bf16 v[74:77], v[160:163], v[216:219], v[74:77]
	s_setprio 0
	s_setprio 1
	v_mfma_f32_16x16x32_bf16 v[118:121], v[164:167], v[188:191], v[118:121]
	v_mfma_f32_16x16x32_bf16 v[114:117], v[172:175], v[188:191], v[114:117]
	v_mfma_f32_16x16x32_bf16 v[102:105], v[164:167], v[196:199], v[102:105]
	v_mfma_f32_16x16x32_bf16 v[98:101], v[172:175], v[196:199], v[98:101]
	v_mfma_f32_16x16x32_bf16 v[86:89], v[164:167], v[204:207], v[86:89]
	v_mfma_f32_16x16x32_bf16 v[82:85], v[172:175], v[204:207], v[82:85]
	v_mfma_f32_16x16x32_bf16 v[70:73], v[164:167], v[212:215], v[70:73]
	v_mfma_f32_16x16x32_bf16 v[66:69], v[172:175], v[212:215], v[66:69]
	v_mfma_f32_16x16x32_bf16 v[118:121], v[168:171], v[192:195], v[118:121]
	v_mfma_f32_16x16x32_bf16 v[114:117], v[176:179], v[192:195], v[114:117]
	v_mfma_f32_16x16x32_bf16 v[102:105], v[168:171], v[200:203], v[102:105]
	v_mfma_f32_16x16x32_bf16 v[98:101], v[176:179], v[200:203], v[98:101]
	v_mfma_f32_16x16x32_bf16 v[86:89], v[168:171], v[208:211], v[86:89]
	v_mfma_f32_16x16x32_bf16 v[82:85], v[176:179], v[208:211], v[82:85]
	v_mfma_f32_16x16x32_bf16 v[70:73], v[168:171], v[216:219], v[70:73]
	v_mfma_f32_16x16x32_bf16 v[66:69], v[176:179], v[216:219], v[66:69]
	s_setprio 0
	s_barrier
	s_add_i32 s53, s44, s30
	v_lshl_add_u64 v[180:181], s[26:27], 0, v[130:131]
	s_mov_b32 m0, s53
	ds_read_b128 v[188:191], v155 offset:16384
	ds_read_b128 v[192:195], v155 offset:17408
	ds_read_b128 v[196:199], v155 offset:18432
	ds_read_b128 v[200:203], v155 offset:19456
	ds_read_b128 v[204:207], v155 offset:20480
	ds_read_b128 v[208:211], v155 offset:21504
	ds_read_b128 v[212:215], v155 offset:22528
	ds_read_b128 v[216:219], v155 offset:23552
	global_load_lds_dwordx4 v[180:181], off
	s_add_i32 m0, s53, 0x2000
	s_add_u32 s54, s26, 0x20000
	v_lshl_add_u64 v[220:221], s[26:27], 0, v[132:133]
	s_addc_u32 s55, s27, 0
	s_add_i32 s53, s45, s30
	global_load_lds_dwordx4 v[220:221], off
	v_lshl_add_u64 v[222:223], s[54:55], 0, v[130:131]
	s_mov_b32 m0, s53
	v_lshl_add_u64 v[224:225], s[28:29], 0, v[132:133]
	global_load_lds_dwordx4 v[222:223], off
	v_lshl_add_u64 v[222:223], s[54:55], 0, v[132:133]
	s_add_i32 m0, s53, 0x2000
	s_nop 0
	global_load_lds_dwordx4 v[222:223], off
	v_lshl_add_u64 v[222:223], s[28:29], 0, v[130:131]
	s_mov_b32 m0, s23
	s_nop 0
	global_load_lds_dwordx4 v[222:223], off
	s_mov_b32 m0, s31
	s_nop 0
	global_load_lds_dwordx4 v[224:225], off
	s_waitcnt vmcnt(8)
	s_waitcnt lgkmcnt(0)
	s_barrier
; #define PG8_STAGE(bufoff, gbase) do { _Pragma("unroll") for (int _i = 0; _i < 2; ++_i) \
;         __builtin_amdgcn_global_load_lds((const unsigned*)((const char*)(gbase) + voff[_i]), (LAS unsigned*)(lds + (bufoff) + ldsw + _i * 8192), 16, 0, 0); } while (0)
; #define PG8_LDA(dst, b, h) do { _Pragma("unroll") for (int m = 0; m < 4; ++m) _Pragma("unroll") for (int k = 0; k < 2; ++k) dst[m][k] = *(const LAS bf16x8*)(lds + PG8_SA(b, h) + aoff + m * 2048 + k * 1024); } while (0)
; #define PG8_LDB(dst, b, h) do { _Pragma("unroll") for (int n = 0; n < 2; ++n) _Pragma("unroll") for (int k = 0; k < 2; ++k) dst[n][k] = *(const LAS bf16x8*)(lds + PG8_SB(b, h) + boff + n * 2048 + k * 1024); } while (0)
; #define PG8_MMA(ai, bj, At, Bt) do { __builtin_amdgcn_s_setprio(1); _Pragma("unroll") for (int m = 0; m < 4; ++m) _Pragma("unroll") for (int n = 0; n < 2; ++n) _Pragma("unroll") for (int k = 0; k < 2; ++k) \
;         acc[ai][bj][m][n] = __builtin_amdgcn_mfma_f32_16x16x32_bf16(Bt[n][k], At[m][k], acc[ai][bj][m][n], 0, 0, 0); __builtin_amdgcn_s_setprio(0); } while (0)
; #define PG8_WAIT_V(n) asm volatile("s_waitcnt vmcnt(" #n ")" ::: "memory")
; #define PG8_WAIT_L(n) asm volatile("s_waitcnt lgkmcnt(" #n ")" ::: "memory")
; #define PG8_BAR __builtin_amdgcn_s_barrier()
; #define PG8_SCHED __builtin_amdgcn_sched_barrier(0)
; template <int EPI> ...
;     ...
;             PG8_WAIT_V(8); PG8_WAIT_L(0); PG8_BAR; PG8_MMA(1, 0, At, B0); PG8_MMA(1, 1, At, B1); PG8_BAR; PG8_SCHED;
;             PG8_LDB(B0, 1, 0); PG8_LDB(B1, 1, 1); PG8_SCHED; PG8_LDA(At, 1, 0); PG8_STAGE(PG8_SA(0, 1), a2 + hstep);
;             PG8_WAIT_V(8); PG8_WAIT_L(0); PG8_BAR; PG8_MMA(0, 0, At, B0); PG8_MMA(0, 1, At, B1); PG8_BAR; PG8_SCHED;
	s_setprio 1
	v_mfma_f32_16x16x32_bf16 v[62:65], v[142:145], v[188:191], v[62:65]
	v_mfma_f32_16x16x32_bf16 v[58:61], v[156:159], v[188:191], v[58:61]
	v_mfma_f32_16x16x32_bf16 v[46:49], v[142:145], v[196:199], v[46:49]
	v_mfma_f32_16x16x32_bf16 v[42:45], v[156:159], v[196:199], v[42:45]
	v_mfma_f32_16x16x32_bf16 v[30:33], v[142:145], v[204:207], v[30:33]
	v_mfma_f32_16x16x32_bf16 v[26:29], v[156:159], v[204:207], v[26:29]
	v_mfma_f32_16x16x32_bf16 v[14:17], v[142:145], v[212:215], v[14:17]
	v_mfma_f32_16x16x32_bf16 v[10:13], v[156:159], v[212:215], v[10:13]
	v_mfma_f32_16x16x32_bf16 v[62:65], v[146:149], v[192:195], v[62:65]
	v_mfma_f32_16x16x32_bf16 v[58:61], v[160:163], v[192:195], v[58:61]
	v_mfma_f32_16x16x32_bf16 v[46:49], v[146:149], v[200:203], v[46:49]
	v_mfma_f32_16x16x32_bf16 v[42:45], v[160:163], v[200:203], v[42:45]
	v_mfma_f32_16x16x32_bf16 v[30:33], v[146:149], v[208:211], v[30:33]
	v_mfma_f32_16x16x32_bf16 v[26:29], v[160:163], v[208:211], v[26:29]
	v_mfma_f32_16x16x32_bf16 v[14:17], v[146:149], v[216:219], v[14:17]
	v_mfma_f32_16x16x32_bf16 v[10:13], v[160:163], v[216:219], v[10:13]
	s_setprio 0
	s_setprio 1
	v_mfma_f32_16x16x32_bf16 v[54:57], v[164:167], v[188:191], v[54:57]
	v_mfma_f32_16x16x32_bf16 v[50:53], v[172:175], v[188:191], v[50:53]
	v_mfma_f32_16x16x32_bf16 v[38:41], v[164:167], v[196:199], v[38:41]
	v_mfma_f32_16x16x32_bf16 v[34:37], v[172:175], v[196:199], v[34:37]
	v_mfma_f32_16x16x32_bf16 v[22:25], v[164:167], v[204:207], v[22:25]
	v_mfma_f32_16x16x32_bf16 v[18:21], v[172:175], v[204:207], v[18:21]
	v_mfma_f32_16x16x32_bf16 v[6:9], v[164:167], v[212:215], v[6:9]
	v_mfma_f32_16x16x32_bf16 v[2:5], v[172:175], v[212:215], v[2:5]
	v_mfma_f32_16x16x32_bf16 v[54:57], v[168:171], v[192:195], v[54:57]
	v_mfma_f32_16x16x32_bf16 v[50:53], v[176:179], v[192:195], v[50:53]
	v_mfma_f32_16x16x32_bf16 v[38:41], v[168:171], v[200:203], v[38:41]
	v_mfma_f32_16x16x32_bf16 v[34:37], v[176:179], v[200:203], v[34:37]
	v_mfma_f32_16x16x32_bf16 v[22:25], v[168:171], v[208:211], v[22:25]
	v_mfma_f32_16x16x32_bf16 v[18:21], v[176:179], v[208:211], v[18:21]
	v_mfma_f32_16x16x32_bf16 v[6:9], v[168:171], v[216:219], v[6:9]
	v_mfma_f32_16x16x32_bf16 v[2:5], v[176:179], v[216:219], v[2:5]
	s_setprio 0
	s_barrier
	s_add_i32 s53, 0, 0x18000
	s_add_i32 s54, 0, 0x1c000
	v_add_u32_e32 v160, s53, v151
	v_add_u32_e32 v176, s54, v151
	ds_read_b128 v[142:145], v160
	ds_read_b128 v[146:149], v160 offset:1024
	ds_read_b128 v[156:159], v160 offset:2048
	ds_read_b128 v[160:163], v160 offset:3072
	ds_read_b128 v[164:167], v176
	ds_read_b128 v[168:171], v176 offset:1024
	ds_read_b128 v[172:175], v176 offset:2048
	ds_read_b128 v[176:179], v176 offset:3072
	s_add_u32 s28, s28, 0x20000
	s_addc_u32 s29, s29, 0
	s_mov_b32 m0, s38
	v_lshl_add_u64 v[226:227], s[28:29], 0, v[130:131]
	ds_read_b128 v[188:191], v155 offset:32768
	ds_read_b128 v[192:195], v155 offset:33792
	ds_read_b128 v[196:199], v155 offset:34816
	ds_read_b128 v[200:203], v155 offset:35840
	ds_read_b128 v[204:207], v155 offset:36864
	ds_read_b128 v[208:211], v155 offset:37888
	ds_read_b128 v[212:215], v155 offset:38912
	ds_read_b128 v[216:219], v155 offset:39936
	global_load_lds_dwordx4 v[226:227], off
	v_lshl_add_u64 v[226:227], s[28:29], 0, v[132:133]
	s_mov_b32 m0, s39
	s_nop 0
	global_load_lds_dwordx4 v[226:227], off
	s_waitcnt vmcnt(8)
	s_waitcnt lgkmcnt(0)
	s_barrier
	s_setprio 1
	v_mfma_f32_16x16x32_bf16 v[126:129], v[142:145], v[188:191], v[126:129]
	v_mfma_f32_16x16x32_bf16 v[122:125], v[156:159], v[188:191], v[122:125]
	v_mfma_f32_16x16x32_bf16 v[110:113], v[142:145], v[196:199], v[110:113]
	v_mfma_f32_16x16x32_bf16 v[106:109], v[156:159], v[196:199], v[106:109]
	v_mfma_f32_16x16x32_bf16 v[94:97], v[142:145], v[204:207], v[94:97]
	v_mfma_f32_16x16x32_bf16 v[90:93], v[156:159], v[204:207], v[90:93]
	v_mfma_f32_16x16x32_bf16 v[78:81], v[142:145], v[212:215], v[78:81]
	v_mfma_f32_16x16x32_bf16 v[74:77], v[156:159], v[212:215], v[74:77]
	v_mfma_f32_16x16x32_bf16 v[126:129], v[146:149], v[192:195], v[126:129]
	v_mfma_f32_16x16x32_bf16 v[122:125], v[160:163], v[192:195], v[122:125]
	v_mfma_f32_16x16x32_bf16 v[110:113], v[146:149], v[200:203], v[110:113]
	v_mfma_f32_16x16x32_bf16 v[106:109], v[160:163], v[200:203], v[106:109]
	v_mfma_f32_16x16x32_bf16 v[94:97], v[146:149], v[208:211], v[94:97]
	v_mfma_f32_16x16x32_bf16 v[90:93], v[160:163], v[208:211], v[90:93]
	v_mfma_f32_16x16x32_bf16 v[78:81], v[146:149], v[216:219], v[78:81]
	v_mfma_f32_16x16x32_bf16 v[74:77], v[160:163], v[216:219], v[74:77]
	s_setprio 0
	s_setprio 1
	v_mfma_f32_16x16x32_bf16 v[118:121], v[164:167], v[188:191], v[118:121]
	v_mfma_f32_16x16x32_bf16 v[114:117], v[172:175], v[188:191], v[114:117]
	v_mfma_f32_16x16x32_bf16 v[102:105], v[164:167], v[196:199], v[102:105]
	v_mfma_f32_16x16x32_bf16 v[98:101], v[172:175], v[196:199], v[98:101]
	v_mfma_f32_16x16x32_bf16 v[86:89], v[164:167], v[204:207], v[86:89]
	v_mfma_f32_16x16x32_bf16 v[82:85], v[172:175], v[204:207], v[82:85]
	v_mfma_f32_16x16x32_bf16 v[70:73], v[164:167], v[212:215], v[70:73]
	v_mfma_f32_16x16x32_bf16 v[66:69], v[172:175], v[212:215], v[66:69]
	v_mfma_f32_16x16x32_bf16 v[118:121], v[168:171], v[192:195], v[118:121]
	v_mfma_f32_16x16x32_bf16 v[114:117], v[176:179], v[192:195], v[114:117]
	v_mfma_f32_16x16x32_bf16 v[102:105], v[168:171], v[200:203], v[102:105]
	v_mfma_f32_16x16x32_bf16 v[98:101], v[176:179], v[200:203], v[98:101]
	v_mfma_f32_16x16x32_bf16 v[86:89], v[168:171], v[208:211], v[86:89]
	v_mfma_f32_16x16x32_bf16 v[82:85], v[176:179], v[208:211], v[82:85]
	v_mfma_f32_16x16x32_bf16 v[70:73], v[168:171], v[216:219], v[70:73]
	v_mfma_f32_16x16x32_bf16 v[66:69], v[176:179], v[216:219], v[66:69]
	s_setprio 0
	s_barrier
; #define PG8_STAGE(bufoff, gbase) do { _Pragma("unroll") for (int _i = 0; _i < 2; ++_i) \
;         __builtin_amdgcn_global_load_lds((const unsigned*)((const char*)(gbase) + voff[_i]), (LAS unsigned*)(lds + (bufoff) + ldsw + _i * 8192), 16, 0, 0); } while (0)
; #define PG8_LDA(dst, b, h) do { _Pragma("unroll") for (int m = 0; m < 4; ++m) _Pragma("unroll") for (int k = 0; k < 2; ++k) dst[m][k] = *(const LAS bf16x8*)(lds + PG8_SA(b, h) + aoff + m * 2048 + k * 1024); } while (0)
; #define PG8_MMA(ai, bj, At, Bt) do { __builtin_amdgcn_s_setprio(1); _Pragma("unroll") for (int m = 0; m < 4; ++m) _Pragma("unroll") for (int n = 0; n < 2; ++n) _Pragma("unroll") for (int k = 0; k < 2; ++k) \
;         acc[ai][bj][m][n] = __builtin_amdgcn_mfma_f32_16x16x32_bf16(Bt[n][k], At[m][k], acc[ai][bj][m][n], 0, 0, 0); __builtin_amdgcn_s_setprio(0); } while (0)
; #define PG8_WAIT_V(n) asm volatile("s_waitcnt vmcnt(" #n ")" ::: "memory")
; #define PG8_WAIT_L(n) asm volatile("s_waitcnt lgkmcnt(" #n ")" ::: "memory")
; #define PG8_BAR __builtin_amdgcn_s_barrier()
; #define PG8_SCHED __builtin_amdgcn_sched_barrier(0)
; template <int EPI> ...
;     ...
;             PG8_LDA(At, 1, 1); PG8_STAGE(PG8_SB(1, 0), b3); PG8_STAGE(PG8_SB(1, 1), b3 + hstep); PG8_STAGE(PG8_SA(1, 0), a3);
;             PG8_WAIT_V(8); PG8_WAIT_L(0); PG8_BAR; PG8_MMA(1, 0, At, B0); PG8_MMA(1, 1, At, B1); PG8_BAR; PG8_SCHED;
;         }
;         if (wr == 0) PG8_BAR;
	s_add_i32 s28, s53, s30
	v_lshl_add_u64 v[180:181], v[180:181], 0, s[6:7]
	s_mov_b32 m0, s28
	ds_read_b128 v[188:191], v155 offset:49152
	ds_read_b128 v[192:195], v155 offset:50176
	ds_read_b128 v[196:199], v155 offset:51200
	ds_read_b128 v[200:203], v155 offset:52224
	ds_read_b128 v[204:207], v155 offset:53248
	ds_read_b128 v[208:211], v155 offset:54272
	ds_read_b128 v[212:215], v155 offset:55296
	ds_read_b128 v[216:219], v155 offset:56320
	global_load_lds_dwordx4 v[180:181], off
	s_add_i32 m0, s28, 0x2000
	s_add_u32 s26, s26, 0x20080
	v_lshl_add_u64 v[180:181], v[220:221], 0, s[6:7]
	s_addc_u32 s27, s27, 0
	s_add_i32 s28, s54, s30
	global_load_lds_dwordx4 v[180:181], off
	v_lshl_add_u64 v[180:181], s[26:27], 0, v[130:131]
	s_mov_b32 m0, s28
	s_nop 0
	global_load_lds_dwordx4 v[180:181], off
	v_lshl_add_u64 v[180:181], s[26:27], 0, v[132:133]
	s_add_i32 m0, s28, 0x2000
	s_nop 0
	global_load_lds_dwordx4 v[180:181], off
	v_lshl_add_u64 v[180:181], v[222:223], 0, s[6:7]
	s_mov_b32 m0, s41
	s_nop 0
	global_load_lds_dwordx4 v[180:181], off
	v_lshl_add_u64 v[180:181], v[224:225], 0, s[6:7]
	s_mov_b32 m0, s42
	s_nop 0
	global_load_lds_dwordx4 v[180:181], off
	s_waitcnt vmcnt(8)
	s_waitcnt lgkmcnt(0)
	s_barrier
	s_setprio 1
	v_mfma_f32_16x16x32_bf16 v[62:65], v[142:145], v[188:191], v[62:65]
	v_mfma_f32_16x16x32_bf16 v[58:61], v[156:159], v[188:191], v[58:61]
	v_mfma_f32_16x16x32_bf16 v[46:49], v[142:145], v[196:199], v[46:49]
	v_mfma_f32_16x16x32_bf16 v[42:45], v[156:159], v[196:199], v[42:45]
	v_mfma_f32_16x16x32_bf16 v[30:33], v[142:145], v[204:207], v[30:33]
	v_mfma_f32_16x16x32_bf16 v[26:29], v[156:159], v[204:207], v[26:29]
	v_mfma_f32_16x16x32_bf16 v[14:17], v[142:145], v[212:215], v[14:17]
	v_mfma_f32_16x16x32_bf16 v[10:13], v[156:159], v[212:215], v[10:13]
	v_mfma_f32_16x16x32_bf16 v[62:65], v[146:149], v[192:195], v[62:65]
	v_mfma_f32_16x16x32_bf16 v[58:61], v[160:163], v[192:195], v[58:61]
	v_mfma_f32_16x16x32_bf16 v[46:49], v[146:149], v[200:203], v[46:49]
	v_mfma_f32_16x16x32_bf16 v[42:45], v[160:163], v[200:203], v[42:45]
	v_mfma_f32_16x16x32_bf16 v[30:33], v[146:149], v[208:211], v[30:33]
	v_mfma_f32_16x16x32_bf16 v[26:29], v[160:163], v[208:211], v[26:29]
	v_mfma_f32_16x16x32_bf16 v[14:17], v[146:149], v[216:219], v[14:17]
	v_mfma_f32_16x16x32_bf16 v[10:13], v[160:163], v[216:219], v[10:13]
	s_setprio 0
	s_setprio 1
	v_mfma_f32_16x16x32_bf16 v[54:57], v[164:167], v[188:191], v[54:57]
	v_mfma_f32_16x16x32_bf16 v[50:53], v[172:175], v[188:191], v[50:53]
	v_mfma_f32_16x16x32_bf16 v[38:41], v[164:167], v[196:199], v[38:41]
	v_mfma_f32_16x16x32_bf16 v[34:37], v[172:175], v[196:199], v[34:37]
	v_mfma_f32_16x16x32_bf16 v[22:25], v[164:167], v[204:207], v[22:25]
	v_mfma_f32_16x16x32_bf16 v[18:21], v[172:175], v[204:207], v[18:21]
	v_mfma_f32_16x16x32_bf16 v[6:9], v[164:167], v[212:215], v[6:9]
	v_mfma_f32_16x16x32_bf16 v[2:5], v[172:175], v[212:215], v[2:5]
	v_mfma_f32_16x16x32_bf16 v[54:57], v[168:171], v[192:195], v[54:57]
	v_mfma_f32_16x16x32_bf16 v[50:53], v[176:179], v[192:195], v[50:53]
	v_mfma_f32_16x16x32_bf16 v[38:41], v[168:171], v[200:203], v[38:41]
	v_mfma_f32_16x16x32_bf16 v[34:37], v[176:179], v[200:203], v[34:37]
	v_mfma_f32_16x16x32_bf16 v[22:25], v[168:171], v[208:211], v[22:25]
	v_mfma_f32_16x16x32_bf16 v[18:21], v[176:179], v[208:211], v[18:21]
	v_mfma_f32_16x16x32_bf16 v[6:9], v[168:171], v[216:219], v[6:9]
	v_mfma_f32_16x16x32_bf16 v[2:5], v[176:179], v[216:219], v[2:5]
	s_setprio 0
	s_barrier
	s_add_i32 s52, s52, 2
	s_add_u32 s24, s24, 0x100
	s_addc_u32 s25, s25, 0
	s_add_u32 s50, s50, 0x100
	s_addc_u32 s51, s51, 0
	s_cmp_gt_u32 s52, 5
	s_cbranch_scc0 .LBB0_737
	s_and_b64 vcc, exec, s[8:9]
	s_cbranch_vccz .LBB0_740
	s_barrier

; #define PG8_STAGE(bufoff, gbase) do { _Pragma("unroll") for (int _i = 0; _i < 2; ++_i) \
;         __builtin_amdgcn_global_load_lds((const unsigned*)((const char*)(gbase) + voff[_i]), (LAS unsigned*)(lds + (bufoff) + ldsw + _i * 8192), 16, 0, 0); } while (0)
; #define PG8_LDA(dst, b, h) do { _Pragma("unroll") for (int m = 0; m < 4; ++m) _Pragma("unroll") for (int k = 0; k < 2; ++k) dst[m][k] = *(const LAS bf16x8*)(lds + PG8_SA(b, h) + aoff + m * 2048 + k * 1024); } while (0)
; #define PG8_LDB(dst, b, h) do { _Pragma("unroll") for (int n = 0; n < 2; ++n) _Pragma("unroll") for (int k = 0; k < 2; ++k) dst[n][k] = *(const LAS bf16x8*)(lds + PG8_SB(b, h) + boff + n * 2048 + k * 1024); } while (0)
; #define PG8_MMA(ai, bj, At, Bt) do { __builtin_amdgcn_s_setprio(1); _Pragma("unroll") for (int m = 0; m < 4; ++m) _Pragma("unroll") for (int n = 0; n < 2; ++n) _Pragma("unroll") for (int k = 0; k < 2; ++k) \
;         acc[ai][bj][m][n] = __builtin_amdgcn_mfma_f32_16x16x32_bf16(Bt[n][k], At[m][k], acc[ai][bj][m][n], 0, 0, 0); __builtin_amdgcn_s_setprio(0); } while (0)
; #define PG8_WAIT_V(n) asm volatile("s_waitcnt vmcnt(" #n ")" ::: "memory")
; #define PG8_WAIT_L(n) asm volatile("s_waitcnt lgkmcnt(" #n ")" ::: "memory")
; #define PG8_BAR __builtin_amdgcn_s_barrier()
; #define PG8_SCHED __builtin_amdgcn_sched_barrier(0)
; template <int EPI> ...
;     ...
;         for (int t = 0; t < cnk; t += 2) {
;             const bool last = (t == cnk - 2);
;             const char* a1 = cA + (size_t)(t + 1) * kstep;
;             const char* a2 = last ? nA : cA + (size_t)(t + 2) * kstep; const char* b2 = last ? nB : cB + (size_t)(t + 2) * kstep;
;             const char* a3 = a2 + kstep; const char* b3 = b2 + kstep;
;             PG8_LDB(B0, 0, 0); PG8_LDB(B1, 0, 1); PG8_SCHED; PG8_LDA(At, 0, 0); PG8_STAGE(PG8_SA(1, 1), a1 + hstep);
;             PG8_WAIT_V(8); PG8_WAIT_L(0); PG8_BAR; PG8_MMA(0, 0, At, B0); PG8_MMA(0, 1, At, B1); PG8_BAR; PG8_SCHED;
;             PG8_LDA(At, 0, 1); PG8_STAGE(PG8_SB(0, 0), b2); PG8_STAGE(PG8_SB(0, 1), b2 + hstep); PG8_STAGE(PG8_SA(0, 0), a2);
;             PG8_WAIT_V(8); PG8_WAIT_L(0); PG8_BAR; PG8_MMA(1, 0, At, B0); PG8_MMA(1, 1, At, B1); PG8_BAR; PG8_SCHED;
.LBB0_825:
	ds_read_b128 v[142:145], v152
	ds_read_b128 v[156:159], v152 offset:1024
	ds_read_b128 v[160:163], v152 offset:2048
	ds_read_b128 v[164:167], v152 offset:3072
	ds_read_b128 v[168:171], v153
	ds_read_b128 v[172:175], v153 offset:1024
	ds_read_b128 v[176:179], v153 offset:2048
	ds_read_b128 v[188:191], v153 offset:3072
	s_add_i32 s57, s34, 2
	s_add_u32 s35, s30, 0xfffc0080
	s_addc_u32 s36, s31, -1
	s_cmp_eq_u32 s54, s34
	s_cselect_b32 s34, s53, s55
	s_cselect_b32 s37, s5, s36
	s_cselect_b32 s36, s19, s35
	s_cselect_b32 s35, s17, s56
	v_lshl_add_u64 v[146:147], s[30:31], 0, v[136:137]
	s_add_i32 m0, s7, 0xc000
	ds_read_b128 v[192:195], v154
	ds_read_b128 v[196:199], v154 offset:1024
	ds_read_b128 v[200:203], v154 offset:2048
	ds_read_b128 v[204:207], v154 offset:3072
	ds_read_b128 v[208:211], v154 offset:4096
	ds_read_b128 v[212:215], v154 offset:5120
	ds_read_b128 v[216:219], v154 offset:6144
	ds_read_b128 v[220:223], v154 offset:7168
	global_load_lds_dwordx4 v[146:147], off
	v_lshl_add_u64 v[146:147], s[30:31], 0, v[138:139]
	s_add_i32 m0, s7, 0xe000
	s_nop 0
	global_load_lds_dwordx4 v[146:147], off
	s_waitcnt vmcnt(8)
	s_waitcnt lgkmcnt(0)
	s_barrier
	s_setprio 1
	v_mfma_f32_16x16x32_bf16 v[126:129], v[142:145], v[192:195], v[126:129]
	v_mfma_f32_16x16x32_bf16 v[122:125], v[160:163], v[192:195], v[122:125]
	v_mfma_f32_16x16x32_bf16 v[118:121], v[142:145], v[200:203], v[118:121]
	v_mfma_f32_16x16x32_bf16 v[114:117], v[160:163], v[200:203], v[114:117]
	v_mfma_f32_16x16x32_bf16 v[106:109], v[142:145], v[208:211], v[106:109]
	v_mfma_f32_16x16x32_bf16 v[98:101], v[160:163], v[208:211], v[98:101]
	v_mfma_f32_16x16x32_bf16 v[90:93], v[142:145], v[216:219], v[90:93]
	v_mfma_f32_16x16x32_bf16 v[82:85], v[160:163], v[216:219], v[82:85]
	v_mfma_f32_16x16x32_bf16 v[126:129], v[156:159], v[196:199], v[126:129]
	v_mfma_f32_16x16x32_bf16 v[122:125], v[164:167], v[196:199], v[122:125]
	v_mfma_f32_16x16x32_bf16 v[118:121], v[156:159], v[204:207], v[118:121]
	v_mfma_f32_16x16x32_bf16 v[114:117], v[164:167], v[204:207], v[114:117]
	v_mfma_f32_16x16x32_bf16 v[106:109], v[156:159], v[212:215], v[106:109]
	v_mfma_f32_16x16x32_bf16 v[98:101], v[164:167], v[212:215], v[98:101]
	v_mfma_f32_16x16x32_bf16 v[90:93], v[156:159], v[220:223], v[90:93]
	v_mfma_f32_16x16x32_bf16 v[82:85], v[164:167], v[220:223], v[82:85]
	s_setprio 0
	s_setprio 1
	v_mfma_f32_16x16x32_bf16 v[110:113], v[168:171], v[192:195], v[110:113]
	v_mfma_f32_16x16x32_bf16 v[102:105], v[176:179], v[192:195], v[102:105]
	v_mfma_f32_16x16x32_bf16 v[94:97], v[168:171], v[200:203], v[94:97]
	v_mfma_f32_16x16x32_bf16 v[86:89], v[176:179], v[200:203], v[86:89]
	v_mfma_f32_16x16x32_bf16 v[78:81], v[168:171], v[208:211], v[78:81]
	v_mfma_f32_16x16x32_bf16 v[74:77], v[176:179], v[208:211], v[74:77]
	v_mfma_f32_16x16x32_bf16 v[70:73], v[168:171], v[216:219], v[70:73]
	v_mfma_f32_16x16x32_bf16 v[66:69], v[176:179], v[216:219], v[66:69]
	v_mfma_f32_16x16x32_bf16 v[110:113], v[172:175], v[196:199], v[110:113]
	v_mfma_f32_16x16x32_bf16 v[102:105], v[188:191], v[196:199], v[102:105]
	v_mfma_f32_16x16x32_bf16 v[94:97], v[172:175], v[204:207], v[94:97]
	v_mfma_f32_16x16x32_bf16 v[86:89], v[188:191], v[204:207], v[86:89]
	v_mfma_f32_16x16x32_bf16 v[78:81], v[172:175], v[212:215], v[78:81]
	v_mfma_f32_16x16x32_bf16 v[74:77], v[188:191], v[212:215], v[74:77]
	v_mfma_f32_16x16x32_bf16 v[70:73], v[172:175], v[220:223], v[70:73]
	v_mfma_f32_16x16x32_bf16 v[66:69], v[188:191], v[220:223], v[66:69]
	s_setprio 0
	s_barrier
	s_add_i32 s58, s46, s39
	v_lshl_add_u64 v[146:147], s[34:35], 0, v[130:131]
	s_mov_b32 m0, s58
	ds_read_b128 v[192:195], v154 offset:16384
	ds_read_b128 v[196:199], v154 offset:17408
	ds_read_b128 v[200:203], v154 offset:18432
	ds_read_b128 v[204:207], v154 offset:19456
	ds_read_b128 v[208:211], v154 offset:20480
	ds_read_b128 v[212:215], v154 offset:21504
	ds_read_b128 v[216:219], v154 offset:22528
	ds_read_b128 v[220:223], v154 offset:23552
	global_load_lds_dwordx4 v[146:147], off
	s_add_i32 m0, s58, 0x2000
	s_add_u32 s58, s34, 0x40000
	v_lshl_add_u64 v[180:181], s[34:35], 0, v[132:133]
	s_addc_u32 s59, s35, 0
	s_add_i32 s60, s47, s39
	global_load_lds_dwordx4 v[180:181], off
	v_lshl_add_u64 v[224:225], s[58:59], 0, v[130:131]
	s_mov_b32 m0, s60
	v_lshl_add_u64 v[226:227], s[36:37], 0, v[132:133]
	global_load_lds_dwordx4 v[224:225], off
	v_lshl_add_u64 v[224:225], s[58:59], 0, v[132:133]
	s_add_i32 m0, s60, 0x2000
	s_nop 0
	global_load_lds_dwordx4 v[224:225], off
	v_lshl_add_u64 v[224:225], s[36:37], 0, v[130:131]
	s_mov_b32 m0, s7
	s_nop 0
	global_load_lds_dwordx4 v[224:225], off
	s_mov_b32 m0, s40
	s_nop 0
	global_load_lds_dwordx4 v[226:227], off
	s_waitcnt vmcnt(8)
	s_waitcnt lgkmcnt(0)
	s_barrier
; #define PG8_STAGE(bufoff, gbase) do { _Pragma("unroll") for (int _i = 0; _i < 2; ++_i) \
;         __builtin_amdgcn_global_load_lds((const unsigned*)((const char*)(gbase) + voff[_i]), (LAS unsigned*)(lds + (bufoff) + ldsw + _i * 8192), 16, 0, 0); } while (0)
; #define PG8_LDA(dst, b, h) do { _Pragma("unroll") for (int m = 0; m < 4; ++m) _Pragma("unroll") for (int k = 0; k < 2; ++k) dst[m][k] = *(const LAS bf16x8*)(lds + PG8_SA(b, h) + aoff + m * 2048 + k * 1024); } while (0)
; #define PG8_LDB(dst, b, h) do { _Pragma("unroll") for (int n = 0; n < 2; ++n) _Pragma("unroll") for (int k = 0; k < 2; ++k) dst[n][k] = *(const LAS bf16x8*)(lds + PG8_SB(b, h) + boff + n * 2048 + k * 1024); } while (0)
; #define PG8_MMA(ai, bj, At, Bt) do { __builtin_amdgcn_s_setprio(1); _Pragma("unroll") for (int m = 0; m < 4; ++m) _Pragma("unroll") for (int n = 0; n < 2; ++n) _Pragma("unroll") for (int k = 0; k < 2; ++k) \
;         acc[ai][bj][m][n] = __builtin_amdgcn_mfma_f32_16x16x32_bf16(Bt[n][k], At[m][k], acc[ai][bj][m][n], 0, 0, 0); __builtin_amdgcn_s_setprio(0); } while (0)
; #define PG8_WAIT_V(n) asm volatile("s_waitcnt vmcnt(" #n ")" ::: "memory")
; #define PG8_WAIT_L(n) asm volatile("s_waitcnt lgkmcnt(" #n ")" ::: "memory")
; #define PG8_BAR __builtin_amdgcn_s_barrier()
; #define PG8_SCHED __builtin_amdgcn_sched_barrier(0)
; template <int EPI> ...
;     ...
;             PG8_WAIT_V(8); PG8_WAIT_L(0); PG8_BAR; PG8_MMA(1, 0, At, B0); PG8_MMA(1, 1, At, B1); PG8_BAR; PG8_SCHED;
;             PG8_LDB(B0, 1, 0); PG8_LDB(B1, 1, 1); PG8_SCHED; PG8_LDA(At, 1, 0); PG8_STAGE(PG8_SA(0, 1), a2 + hstep);
;             PG8_WAIT_V(8); PG8_WAIT_L(0); PG8_BAR; PG8_MMA(0, 0, At, B0); PG8_MMA(0, 1, At, B1); PG8_BAR; PG8_SCHED;
	s_setprio 1
	v_mfma_f32_16x16x32_bf16 v[62:65], v[142:145], v[192:195], v[62:65]
	v_mfma_f32_16x16x32_bf16 v[58:61], v[160:163], v[192:195], v[58:61]
	v_mfma_f32_16x16x32_bf16 v[54:57], v[142:145], v[200:203], v[54:57]
	v_mfma_f32_16x16x32_bf16 v[50:53], v[160:163], v[200:203], v[50:53]
	v_mfma_f32_16x16x32_bf16 v[42:45], v[142:145], v[208:211], v[42:45]
	v_mfma_f32_16x16x32_bf16 v[34:37], v[160:163], v[208:211], v[34:37]
	v_mfma_f32_16x16x32_bf16 v[26:29], v[142:145], v[216:219], v[26:29]
	v_mfma_f32_16x16x32_bf16 v[18:21], v[160:163], v[216:219], v[18:21]
	v_mfma_f32_16x16x32_bf16 v[62:65], v[156:159], v[196:199], v[62:65]
	v_mfma_f32_16x16x32_bf16 v[58:61], v[164:167], v[196:199], v[58:61]
	v_mfma_f32_16x16x32_bf16 v[54:57], v[156:159], v[204:207], v[54:57]
	v_mfma_f32_16x16x32_bf16 v[50:53], v[164:167], v[204:207], v[50:53]
	v_mfma_f32_16x16x32_bf16 v[42:45], v[156:159], v[212:215], v[42:45]
	v_mfma_f32_16x16x32_bf16 v[34:37], v[164:167], v[212:215], v[34:37]
	v_mfma_f32_16x16x32_bf16 v[26:29], v[156:159], v[220:223], v[26:29]
	v_mfma_f32_16x16x32_bf16 v[18:21], v[164:167], v[220:223], v[18:21]
	s_setprio 0
	s_setprio 1
	v_mfma_f32_16x16x32_bf16 v[46:49], v[168:171], v[192:195], v[46:49]
	v_mfma_f32_16x16x32_bf16 v[38:41], v[176:179], v[192:195], v[38:41]
	v_mfma_f32_16x16x32_bf16 v[30:33], v[168:171], v[200:203], v[30:33]
	v_mfma_f32_16x16x32_bf16 v[22:25], v[176:179], v[200:203], v[22:25]
	v_mfma_f32_16x16x32_bf16 v[14:17], v[168:171], v[208:211], v[14:17]
	v_mfma_f32_16x16x32_bf16 v[10:13], v[176:179], v[208:211], v[10:13]
	v_mfma_f32_16x16x32_bf16 v[6:9], v[168:171], v[216:219], v[6:9]
	v_mfma_f32_16x16x32_bf16 v[2:5], v[176:179], v[216:219], v[2:5]
	v_mfma_f32_16x16x32_bf16 v[46:49], v[172:175], v[196:199], v[46:49]
	v_mfma_f32_16x16x32_bf16 v[38:41], v[188:191], v[196:199], v[38:41]
	v_mfma_f32_16x16x32_bf16 v[30:33], v[172:175], v[204:207], v[30:33]
	v_mfma_f32_16x16x32_bf16 v[22:25], v[188:191], v[204:207], v[22:25]
	v_mfma_f32_16x16x32_bf16 v[14:17], v[172:175], v[212:215], v[14:17]
	v_mfma_f32_16x16x32_bf16 v[10:13], v[188:191], v[212:215], v[10:13]
	v_mfma_f32_16x16x32_bf16 v[6:9], v[172:175], v[220:223], v[6:9]
	v_mfma_f32_16x16x32_bf16 v[2:5], v[188:191], v[220:223], v[2:5]
	s_setprio 0
	s_barrier
	s_add_i32 s58, 0, 0x18000
	v_add_u32_e32 v155, s58, v149
	s_add_i32 s59, 0, 0x1c000
	ds_read_b128 v[142:145], v155
	ds_read_b128 v[156:159], v155 offset:1024
	ds_read_b128 v[160:163], v155 offset:2048
	ds_read_b128 v[164:167], v155 offset:3072
	v_add_u32_e32 v155, s59, v149
	ds_read_b128 v[168:171], v155
	ds_read_b128 v[172:175], v155 offset:1024
	ds_read_b128 v[176:179], v155 offset:2048
	ds_read_b128 v[188:191], v155 offset:3072
	s_add_u32 s36, s36, 0x40000
	s_addc_u32 s37, s37, 0
	s_mov_b32 m0, s41
	v_lshl_add_u64 v[228:229], s[36:37], 0, v[130:131]
	ds_read_b128 v[192:195], v154 offset:32768
	ds_read_b128 v[196:199], v154 offset:33792
	ds_read_b128 v[200:203], v154 offset:34816
	ds_read_b128 v[204:207], v154 offset:35840
	ds_read_b128 v[208:211], v154 offset:36864
	ds_read_b128 v[212:215], v154 offset:37888
	ds_read_b128 v[216:219], v154 offset:38912
	ds_read_b128 v[220:223], v154 offset:39936
	global_load_lds_dwordx4 v[228:229], off
	v_lshl_add_u64 v[228:229], s[36:37], 0, v[132:133]
	s_mov_b32 m0, s42
	s_nop 0
	global_load_lds_dwordx4 v[228:229], off
	s_waitcnt vmcnt(8)
	s_waitcnt lgkmcnt(0)
	s_barrier
	s_setprio 1
	v_mfma_f32_16x16x32_bf16 v[126:129], v[142:145], v[192:195], v[126:129]
	v_mfma_f32_16x16x32_bf16 v[122:125], v[160:163], v[192:195], v[122:125]
	v_mfma_f32_16x16x32_bf16 v[118:121], v[142:145], v[200:203], v[118:121]
	v_mfma_f32_16x16x32_bf16 v[114:117], v[160:163], v[200:203], v[114:117]
	v_mfma_f32_16x16x32_bf16 v[106:109], v[142:145], v[208:211], v[106:109]
	v_mfma_f32_16x16x32_bf16 v[98:101], v[160:163], v[208:211], v[98:101]
	v_mfma_f32_16x16x32_bf16 v[90:93], v[142:145], v[216:219], v[90:93]
	v_mfma_f32_16x16x32_bf16 v[82:85], v[160:163], v[216:219], v[82:85]
	v_mfma_f32_16x16x32_bf16 v[126:129], v[156:159], v[196:199], v[126:129]
	v_mfma_f32_16x16x32_bf16 v[122:125], v[164:167], v[196:199], v[122:125]
	v_mfma_f32_16x16x32_bf16 v[118:121], v[156:159], v[204:207], v[118:121]
	v_mfma_f32_16x16x32_bf16 v[114:117], v[164:167], v[204:207], v[114:117]
	v_mfma_f32_16x16x32_bf16 v[106:109], v[156:159], v[212:215], v[106:109]
	v_mfma_f32_16x16x32_bf16 v[98:101], v[164:167], v[212:215], v[98:101]
	v_mfma_f32_16x16x32_bf16 v[90:93], v[156:159], v[220:223], v[90:93]
	v_mfma_f32_16x16x32_bf16 v[82:85], v[164:167], v[220:223], v[82:85]
	s_setprio 0
	s_setprio 1
	v_mfma_f32_16x16x32_bf16 v[110:113], v[168:171], v[192:195], v[110:113]
	v_mfma_f32_16x16x32_bf16 v[102:105], v[176:179], v[192:195], v[102:105]
	v_mfma_f32_16x16x32_bf16 v[94:97], v[168:171], v[200:203], v[94:97]
	v_mfma_f32_16x16x32_bf16 v[86:89], v[176:179], v[200:203], v[86:89]
	v_mfma_f32_16x16x32_bf16 v[78:81], v[168:171], v[208:211], v[78:81]
	v_mfma_f32_16x16x32_bf16 v[74:77], v[176:179], v[208:211], v[74:77]
	v_mfma_f32_16x16x32_bf16 v[70:73], v[168:171], v[216:219], v[70:73]
	v_mfma_f32_16x16x32_bf16 v[66:69], v[176:179], v[216:219], v[66:69]
	v_mfma_f32_16x16x32_bf16 v[110:113], v[172:175], v[196:199], v[110:113]
	v_mfma_f32_16x16x32_bf16 v[102:105], v[188:191], v[196:199], v[102:105]
	v_mfma_f32_16x16x32_bf16 v[94:97], v[172:175], v[204:207], v[94:97]
	v_mfma_f32_16x16x32_bf16 v[86:89], v[188:191], v[204:207], v[86:89]
	v_mfma_f32_16x16x32_bf16 v[78:81], v[172:175], v[212:215], v[78:81]
	v_mfma_f32_16x16x32_bf16 v[74:77], v[188:191], v[212:215], v[74:77]
	v_mfma_f32_16x16x32_bf16 v[70:73], v[172:175], v[220:223], v[70:73]
	v_mfma_f32_16x16x32_bf16 v[66:69], v[188:191], v[220:223], v[66:69]
	s_setprio 0
	s_barrier
; #define PG8_STAGE(bufoff, gbase) do { _Pragma("unroll") for (int _i = 0; _i < 2; ++_i) \
;         __builtin_amdgcn_global_load_lds((const unsigned*)((const char*)(gbase) + voff[_i]), (LAS unsigned*)(lds + (bufoff) + ldsw + _i * 8192), 16, 0, 0); } while (0)
; #define PG8_LDA(dst, b, h) do { _Pragma("unroll") for (int m = 0; m < 4; ++m) _Pragma("unroll") for (int k = 0; k < 2; ++k) dst[m][k] = *(const LAS bf16x8*)(lds + PG8_SA(b, h) + aoff + m * 2048 + k * 1024); } while (0)
; #define PG8_MMA(ai, bj, At, Bt) do { __builtin_amdgcn_s_setprio(1); _Pragma("unroll") for (int m = 0; m < 4; ++m) _Pragma("unroll") for (int n = 0; n < 2; ++n) _Pragma("unroll") for (int k = 0; k < 2; ++k) \
;         acc[ai][bj][m][n] = __builtin_amdgcn_mfma_f32_16x16x32_bf16(Bt[n][k], At[m][k], acc[ai][bj][m][n], 0, 0, 0); __builtin_amdgcn_s_setprio(0); } while (0)
; #define PG8_WAIT_V(n) asm volatile("s_waitcnt vmcnt(" #n ")" ::: "memory")
; #define PG8_WAIT_L(n) asm volatile("s_waitcnt lgkmcnt(" #n ")" ::: "memory")
; #define PG8_BAR __builtin_amdgcn_s_barrier()
; #define PG8_SCHED __builtin_amdgcn_sched_barrier(0)
; template <int EPI> ...
;     ...
;             PG8_LDA(At, 1, 1); PG8_STAGE(PG8_SB(1, 0), b3); PG8_STAGE(PG8_SB(1, 1), b3 + hstep); PG8_STAGE(PG8_SA(1, 0), a3);
;             PG8_WAIT_V(8); PG8_WAIT_L(0); PG8_BAR; PG8_MMA(1, 0, At, B0); PG8_MMA(1, 1, At, B1); PG8_BAR; PG8_SCHED;
;         }
;         if (wr == 0) PG8_BAR;
;         if (SPLIT && cur_slice >= 0) {
	s_add_i32 s36, s58, s39
	v_lshl_add_u64 v[146:147], v[146:147], 0, s[10:11]
	s_mov_b32 m0, s36
	ds_read_b128 v[192:195], v154 offset:49152
	ds_read_b128 v[196:199], v154 offset:50176
	ds_read_b128 v[200:203], v154 offset:51200
	ds_read_b128 v[204:207], v154 offset:52224
	ds_read_b128 v[208:211], v154 offset:53248
	ds_read_b128 v[212:215], v154 offset:54272
	ds_read_b128 v[216:219], v154 offset:55296
	ds_read_b128 v[220:223], v154 offset:56320
	global_load_lds_dwordx4 v[146:147], off
	s_add_i32 m0, s36, 0x2000
	s_add_u32 s34, s34, 0x40080
	v_lshl_add_u64 v[146:147], v[180:181], 0, s[10:11]
	s_addc_u32 s35, s35, 0
	s_add_i32 s36, s59, s39
	global_load_lds_dwordx4 v[146:147], off
	v_lshl_add_u64 v[146:147], s[34:35], 0, v[130:131]
	s_mov_b32 m0, s36
	s_nop 0
	global_load_lds_dwordx4 v[146:147], off
	v_lshl_add_u64 v[146:147], s[34:35], 0, v[132:133]
	s_add_i32 m0, s36, 0x2000
	s_nop 0
	global_load_lds_dwordx4 v[146:147], off
	v_lshl_add_u64 v[146:147], v[224:225], 0, s[10:11]
	s_mov_b32 m0, s43
	s_nop 0
	global_load_lds_dwordx4 v[146:147], off
	v_lshl_add_u64 v[146:147], v[226:227], 0, s[10:11]
	s_mov_b32 m0, s44
	s_nop 0
	global_load_lds_dwordx4 v[146:147], off
	s_waitcnt vmcnt(8)
	s_waitcnt lgkmcnt(0)
	s_barrier
	s_setprio 1
	v_mfma_f32_16x16x32_bf16 v[62:65], v[142:145], v[192:195], v[62:65]
	v_mfma_f32_16x16x32_bf16 v[58:61], v[160:163], v[192:195], v[58:61]
	v_mfma_f32_16x16x32_bf16 v[54:57], v[142:145], v[200:203], v[54:57]
	v_mfma_f32_16x16x32_bf16 v[50:53], v[160:163], v[200:203], v[50:53]
	v_mfma_f32_16x16x32_bf16 v[42:45], v[142:145], v[208:211], v[42:45]
	v_mfma_f32_16x16x32_bf16 v[34:37], v[160:163], v[208:211], v[34:37]
	v_mfma_f32_16x16x32_bf16 v[26:29], v[142:145], v[216:219], v[26:29]
	v_mfma_f32_16x16x32_bf16 v[18:21], v[160:163], v[216:219], v[18:21]
	v_mfma_f32_16x16x32_bf16 v[62:65], v[156:159], v[196:199], v[62:65]
	v_mfma_f32_16x16x32_bf16 v[58:61], v[164:167], v[196:199], v[58:61]
	v_mfma_f32_16x16x32_bf16 v[54:57], v[156:159], v[204:207], v[54:57]
	v_mfma_f32_16x16x32_bf16 v[50:53], v[164:167], v[204:207], v[50:53]
	v_mfma_f32_16x16x32_bf16 v[42:45], v[156:159], v[212:215], v[42:45]
	v_mfma_f32_16x16x32_bf16 v[34:37], v[164:167], v[212:215], v[34:37]
	v_mfma_f32_16x16x32_bf16 v[26:29], v[156:159], v[220:223], v[26:29]
	v_mfma_f32_16x16x32_bf16 v[18:21], v[164:167], v[220:223], v[18:21]
	s_setprio 0
	s_setprio 1
	v_mfma_f32_16x16x32_bf16 v[46:49], v[168:171], v[192:195], v[46:49]
	v_mfma_f32_16x16x32_bf16 v[38:41], v[176:179], v[192:195], v[38:41]
	v_mfma_f32_16x16x32_bf16 v[30:33], v[168:171], v[200:203], v[30:33]
	v_mfma_f32_16x16x32_bf16 v[22:25], v[176:179], v[200:203], v[22:25]
	v_mfma_f32_16x16x32_bf16 v[14:17], v[168:171], v[208:211], v[14:17]
	v_mfma_f32_16x16x32_bf16 v[10:13], v[176:179], v[208:211], v[10:13]
	v_mfma_f32_16x16x32_bf16 v[6:9], v[168:171], v[216:219], v[6:9]
	v_mfma_f32_16x16x32_bf16 v[2:5], v[176:179], v[216:219], v[2:5]
	v_mfma_f32_16x16x32_bf16 v[46:49], v[172:175], v[196:199], v[46:49]
	v_mfma_f32_16x16x32_bf16 v[38:41], v[188:191], v[196:199], v[38:41]
	v_mfma_f32_16x16x32_bf16 v[30:33], v[172:175], v[204:207], v[30:33]
	v_mfma_f32_16x16x32_bf16 v[22:25], v[188:191], v[204:207], v[22:25]
	v_mfma_f32_16x16x32_bf16 v[14:17], v[172:175], v[212:215], v[14:17]
	v_mfma_f32_16x16x32_bf16 v[10:13], v[188:191], v[212:215], v[10:13]
	v_mfma_f32_16x16x32_bf16 v[6:9], v[172:175], v[220:223], v[6:9]
	v_mfma_f32_16x16x32_bf16 v[2:5], v[188:191], v[220:223], v[2:5]
	s_setprio 0
	s_barrier
	s_add_u32 s30, s30, 0x100
	s_addc_u32 s31, s31, 0
	s_add_u32 s55, s55, 0x100
	s_addc_u32 s56, s56, 0
	s_cmp_ge_u32 s57, s52
	s_mov_b32 s34, s57
	s_cbranch_scc0 .LBB0_825
	s_and_b64 vcc, exec, s[12:13]
	s_cbranch_vccz .LBB0_830
	s_barrier
	s_cmp_lt_i32 s0, 0
	s_mov_b64 s[30:31], -1
	s_cbranch_scc1 .LBB0_831

; #define PG8_STAGE(bufoff, gbase) do { _Pragma("unroll") for (int _i = 0; _i < 2; ++_i) \
;         __builtin_amdgcn_global_load_lds((const unsigned*)((const char*)(gbase) + voff[_i]), (LAS unsigned*)(lds + (bufoff) + ldsw + _i * 8192), 16, 0, 0); } while (0)
; #define PG8_LDA(dst, b, h) do { _Pragma("unroll") for (int m = 0; m < 4; ++m) _Pragma("unroll") for (int k = 0; k < 2; ++k) dst[m][k] = *(const LAS bf16x8*)(lds + PG8_SA(b, h) + aoff + m * 2048 + k * 1024); } while (0)
; #define PG8_MMA(ai, bj, At, Bt) do { __builtin_amdgcn_s_setprio(1); _Pragma("unroll") for (int m = 0; m < 4; ++m) _Pragma("unroll") for (int n = 0; n < 2; ++n) _Pragma("unroll") for (int k = 0; k < 2; ++k) \
;         acc[ai][bj][m][n] = __builtin_amdgcn_mfma_f32_16x16x32_bf16(Bt[n][k], At[m][k], acc[ai][bj][m][n], 0, 0, 0); __builtin_amdgcn_s_setprio(0); } while (0)
; #define PG8_WAIT_V(n) asm volatile("s_waitcnt vmcnt(" #n ")" ::: "memory")
; #define PG8_WAIT_L(n) asm volatile("s_waitcnt lgkmcnt(" #n ")" ::: "memory")
; #define PG8_BAR __builtin_amdgcn_s_barrier()
; #define PG8_SCHED __builtin_amdgcn_sched_barrier(0)
; template <int EPI> ...
;     ...
;             PG8_WAIT_V(8); PG8_WAIT_L(0); PG8_BAR; PG8_MMA(0, 0, At, B0); PG8_MMA(0, 1, At, B1); PG8_BAR; PG8_SCHED;
;             PG8_LDA(At, 0, 1); PG8_STAGE(PG8_SB(0, 0), b2); PG8_STAGE(PG8_SB(0, 1), b2 + hstep); PG8_STAGE(PG8_SA(0, 0), a2);
;             PG8_WAIT_V(8); PG8_WAIT_L(0); PG8_BAR; PG8_MMA(1, 0, At, B0); PG8_MMA(1, 1, At, B1); PG8_BAR; PG8_SCHED;
.Lup_wdone_0:
	s_waitcnt lgkmcnt(0)
	s_barrier
	s_setprio 1
	v_mfma_f32_16x16x32_bf16 v[150:153], v[38:41], v[162:165], v[150:153]
	v_mfma_f32_16x16x32_bf16 v[158:161], v[46:49], v[162:165], v[158:161]
	v_mfma_f32_16x16x32_bf16 v[134:137], v[38:41], v[170:173], v[134:137]
	v_mfma_f32_16x16x32_bf16 v[142:145], v[46:49], v[170:173], v[142:145]
	v_mfma_f32_16x16x32_bf16 v[118:121], v[38:41], v[178:181], v[118:121]
	v_mfma_f32_16x16x32_bf16 v[126:129], v[46:49], v[178:181], v[126:129]
	v_mfma_f32_16x16x32_bf16 v[110:113], v[38:41], v[218:221], v[110:113]
	v_mfma_f32_16x16x32_bf16 v[106:109], v[46:49], v[218:221], v[106:109]
	v_mfma_f32_16x16x32_bf16 v[150:153], v[42:45], v[166:169], v[150:153]
	v_mfma_f32_16x16x32_bf16 v[158:161], v[50:53], v[166:169], v[158:161]
	v_mfma_f32_16x16x32_bf16 v[134:137], v[42:45], v[174:177], v[134:137]
	v_mfma_f32_16x16x32_bf16 v[142:145], v[50:53], v[174:177], v[142:145]
	v_mfma_f32_16x16x32_bf16 v[118:121], v[42:45], v[214:217], v[118:121]
	v_mfma_f32_16x16x32_bf16 v[126:129], v[50:53], v[214:217], v[126:129]
	v_mfma_f32_16x16x32_bf16 v[110:113], v[42:45], v[222:225], v[110:113]
	v_mfma_f32_16x16x32_bf16 v[106:109], v[50:53], v[222:225], v[106:109]
	s_setprio 0
	s_setprio 1
	v_mfma_f32_16x16x32_bf16 v[146:149], v[54:57], v[162:165], v[146:149]
	v_mfma_f32_16x16x32_bf16 v[154:157], v[66:69], v[162:165], v[154:157]
	v_mfma_f32_16x16x32_bf16 v[130:133], v[54:57], v[170:173], v[130:133]
	v_mfma_f32_16x16x32_bf16 v[138:141], v[66:69], v[170:173], v[138:141]
	v_mfma_f32_16x16x32_bf16 v[114:117], v[54:57], v[178:181], v[114:117]
	v_mfma_f32_16x16x32_bf16 v[122:125], v[66:69], v[178:181], v[122:125]
	v_mfma_f32_16x16x32_bf16 v[102:105], v[54:57], v[218:221], v[102:105]
	v_mfma_f32_16x16x32_bf16 v[98:101], v[66:69], v[218:221], v[98:101]
	v_mfma_f32_16x16x32_bf16 v[146:149], v[58:61], v[166:169], v[146:149]
	v_mfma_f32_16x16x32_bf16 v[154:157], v[70:73], v[166:169], v[154:157]
	v_mfma_f32_16x16x32_bf16 v[130:133], v[58:61], v[174:177], v[130:133]
	v_mfma_f32_16x16x32_bf16 v[138:141], v[70:73], v[174:177], v[138:141]
	v_mfma_f32_16x16x32_bf16 v[114:117], v[58:61], v[214:217], v[114:117]
	v_mfma_f32_16x16x32_bf16 v[122:125], v[70:73], v[214:217], v[122:125]
	v_mfma_f32_16x16x32_bf16 v[102:105], v[58:61], v[222:225], v[102:105]
	v_mfma_f32_16x16x32_bf16 v[98:101], v[70:73], v[222:225], v[98:101]
	s_setprio 0
	s_barrier
	s_add_i32 s84, s75, s65
	v_lshl_add_u64 v[230:231], s[58:59], 0, v[194:195]
	s_mov_b32 m0, s84
	ds_read_b128 v[162:165], v193 offset:16384
	ds_read_b128 v[166:169], v193 offset:17408
	ds_read_b128 v[170:173], v193 offset:18432
	ds_read_b128 v[174:177], v193 offset:19456
	ds_read_b128 v[178:181], v193 offset:20480
	ds_read_b128 v[214:217], v193 offset:21504
	ds_read_b128 v[218:221], v193 offset:22528
	ds_read_b128 v[222:225], v193 offset:23552
	global_load_lds_dwordx4 v[230:231], off
	s_add_i32 m0, s84, 0x2000
	s_add_u32 s84, s58, 0x40000
	v_lshl_add_u64 v[232:233], s[58:59], 0, v[196:197]
	s_addc_u32 s85, s59, 0
	s_add_i32 s86, s76, s65
	global_load_lds_dwordx4 v[232:233], off
	v_lshl_add_u64 v[226:227], s[84:85], 0, v[194:195]
	s_mov_b32 m0, s86
	v_lshl_add_u64 v[234:235], s[60:61], 0, v[194:195]
	global_load_lds_dwordx4 v[226:227], off
	v_lshl_add_u64 v[226:227], s[84:85], 0, v[196:197]
	s_add_i32 m0, s86, 0x2000
	v_lshl_add_u64 v[236:237], s[60:61], 0, v[196:197]
	global_load_lds_dwordx4 v[226:227], off
	s_mov_b32 m0, s66
	s_nop 0
	global_load_lds_dwordx4 v[234:235], off
	s_mov_b32 m0, s67
	s_nop 0
	global_load_lds_dwordx4 v[236:237], off
	s_cmp_lg_u32 s83, -2
	s_cbranch_scc1 .Lup_strict_1
	s_cmp_lt_u32 s70, 2
	s_cbranch_scc1 .Lup_strict_1
	s_waitcnt vmcnt(24)
	s_branch .Lup_wdone_1

; #define PG8_STAGE(bufoff, gbase) do { _Pragma("unroll") for (int _i = 0; _i < 2; ++_i) \
;         __builtin_amdgcn_global_load_lds((const unsigned*)((const char*)(gbase) + voff[_i]), (LAS unsigned*)(lds + (bufoff) + ldsw + _i * 8192), 16, 0, 0); } while (0)
; #define PG8_LDA(dst, b, h) do { _Pragma("unroll") for (int m = 0; m < 4; ++m) _Pragma("unroll") for (int k = 0; k < 2; ++k) dst[m][k] = *(const LAS bf16x8*)(lds + PG8_SA(b, h) + aoff + m * 2048 + k * 1024); } while (0)
; #define PG8_LDB(dst, b, h) do { _Pragma("unroll") for (int n = 0; n < 2; ++n) _Pragma("unroll") for (int k = 0; k < 2; ++k) dst[n][k] = *(const LAS bf16x8*)(lds + PG8_SB(b, h) + boff + n * 2048 + k * 1024); } while (0)
; #define PG8_WAIT_V(n) asm volatile("s_waitcnt vmcnt(" #n ")" ::: "memory")
; #define PG8_WAIT_L(n) asm volatile("s_waitcnt lgkmcnt(" #n ")" ::: "memory")
; #define PG8_BAR __builtin_amdgcn_s_barrier()
; #define PG8_SCHED __builtin_amdgcn_sched_barrier(0)
; template <int EPI> ...
;     ...
;         for (int t = 0; t < cnk; t += 2) {
;             const bool last = (t == cnk - 2);
;             const char* a1 = cA + (size_t)(t + 1) * kstep;
;             const char* a2 = last ? nA : cA + (size_t)(t + 2) * kstep; const char* b2 = last ? nB : cB + (size_t)(t + 2) * kstep;
;             const char* a3 = a2 + kstep; const char* b3 = b2 + kstep;
;             PG8_LDB(B0, 0, 0); PG8_LDB(B1, 0, 1); PG8_SCHED; PG8_LDA(At, 0, 0); PG8_STAGE(PG8_SA(1, 1), a1 + hstep);
;             PG8_WAIT_V(8); PG8_WAIT_L(0); PG8_BAR; PG8_MMA(0, 0, At, B0); PG8_MMA(0, 1, At, B1); PG8_BAR; PG8_SCHED;
;             PG8_LDA(At, 0, 1); PG8_STAGE(PG8_SB(0, 0), b2); PG8_STAGE(PG8_SB(0, 1), b2 + hstep); PG8_STAGE(PG8_SA(0, 0), a2);
;             PG8_WAIT_V(8); PG8_WAIT_L(0); PG8_BAR; PG8_MMA(1, 0, At, B0); PG8_MMA(1, 1, At, B1); PG8_BAR; PG8_SCHED;
;             PG8_LDB(B0, 1, 0); PG8_LDB(B1, 1, 1); PG8_SCHED; PG8_LDA(At, 1, 0); PG8_STAGE(PG8_SA(0, 1), a2 + hstep);
;             PG8_WAIT_V(8); PG8_WAIT_L(0); PG8_BAR; PG8_MMA(0, 0, At, B0); PG8_MMA(0, 1, At, B1); PG8_BAR; PG8_SCHED;
;             PG8_LDA(At, 1, 1); PG8_STAGE(PG8_SB(1, 0), b3); PG8_STAGE(PG8_SB(1, 1), b3 + hstep); PG8_STAGE(PG8_SA(1, 0), a3);
;             PG8_WAIT_V(8); PG8_WAIT_L(0); PG8_BAR; PG8_MMA(1, 0, At, B0); PG8_MMA(1, 1, At, B1); PG8_BAR; PG8_SCHED;
.Lup_wdone_1:
	s_waitcnt lgkmcnt(0)
	s_barrier
	s_setprio 1
	v_mfma_f32_16x16x32_bf16 v[86:89], v[38:41], v[162:165], v[86:89]
	v_mfma_f32_16x16x32_bf16 v[94:97], v[46:49], v[162:165], v[94:97]
	v_mfma_f32_16x16x32_bf16 v[62:65], v[38:41], v[170:173], v[62:65]
	v_mfma_f32_16x16x32_bf16 v[78:81], v[46:49], v[170:173], v[78:81]
	v_mfma_f32_16x16x32_bf16 v[22:25], v[38:41], v[178:181], v[22:25]
	v_mfma_f32_16x16x32_bf16 v[30:33], v[46:49], v[178:181], v[30:33]
	v_mfma_f32_16x16x32_bf16 v[14:17], v[38:41], v[218:221], v[14:17]
	v_mfma_f32_16x16x32_bf16 v[10:13], v[46:49], v[218:221], v[10:13]
	v_mfma_f32_16x16x32_bf16 v[86:89], v[42:45], v[166:169], v[86:89]
	v_mfma_f32_16x16x32_bf16 v[94:97], v[50:53], v[166:169], v[94:97]
	v_mfma_f32_16x16x32_bf16 v[62:65], v[42:45], v[174:177], v[62:65]
	v_mfma_f32_16x16x32_bf16 v[78:81], v[50:53], v[174:177], v[78:81]
	v_mfma_f32_16x16x32_bf16 v[22:25], v[42:45], v[214:217], v[22:25]
	v_mfma_f32_16x16x32_bf16 v[30:33], v[50:53], v[214:217], v[30:33]
	v_mfma_f32_16x16x32_bf16 v[14:17], v[42:45], v[222:225], v[14:17]
	v_mfma_f32_16x16x32_bf16 v[10:13], v[50:53], v[222:225], v[10:13]
	s_setprio 0
	s_setprio 1
	v_mfma_f32_16x16x32_bf16 v[34:37], v[54:57], v[170:173], v[34:37]
	v_mfma_f32_16x16x32_bf16 v[18:21], v[54:57], v[178:181], v[18:21]
	v_mfma_f32_16x16x32_bf16 v[26:29], v[66:69], v[178:181], v[26:29]
	v_mfma_f32_16x16x32_bf16 v[6:9], v[54:57], v[218:221], v[6:9]
	v_mfma_f32_16x16x32_bf16 v[2:5], v[66:69], v[218:221], v[2:5]
	v_mfma_f32_16x16x32_bf16 v[38:41], v[54:57], v[162:165], v[82:85]
	v_mfma_f32_16x16x32_bf16 v[42:45], v[66:69], v[162:165], v[90:93]
	v_mfma_f32_16x16x32_bf16 v[34:37], v[58:61], v[174:177], v[34:37]
	v_mfma_f32_16x16x32_bf16 v[46:49], v[66:69], v[170:173], v[74:77]
	v_mfma_f32_16x16x32_bf16 v[18:21], v[58:61], v[214:217], v[18:21]
	v_mfma_f32_16x16x32_bf16 v[26:29], v[70:73], v[214:217], v[26:29]
	v_mfma_f32_16x16x32_bf16 v[6:9], v[58:61], v[222:225], v[6:9]
	v_mfma_f32_16x16x32_bf16 v[2:5], v[70:73], v[222:225], v[2:5]
	v_mfma_f32_16x16x32_bf16 v[38:41], v[58:61], v[166:169], v[38:41]
	v_mfma_f32_16x16x32_bf16 v[42:45], v[70:73], v[166:169], v[42:45]
	v_mfma_f32_16x16x32_bf16 v[46:49], v[70:73], v[174:177], v[46:49]
	s_setprio 0
	s_barrier
	s_add_i32 s84, 0, 0x18000
	s_add_i32 s85, 0, 0x1c000
	v_add_u32_e32 v66, s84, v183
	v_add_u32_e32 v74, s85, v183
	ds_read_b128 v[50:53], v66
	ds_read_b128 v[54:57], v66 offset:1024
	ds_read_b128 v[58:61], v66 offset:2048
	ds_read_b128 v[66:69], v66 offset:3072
	ds_read_b128 v[70:73], v74
	ds_read_b128 v[162:165], v74 offset:1024
	ds_read_b128 v[166:169], v74 offset:2048
	ds_read_b128 v[170:173], v74 offset:3072
	s_add_u32 s60, s60, 0x40000
	s_addc_u32 s61, s61, 0
	s_mov_b32 m0, s68
	v_lshl_add_u64 v[226:227], s[60:61], 0, v[194:195]
	ds_read_b128 v[74:77], v193 offset:32768
	ds_read_b128 v[82:85], v193 offset:33792
	ds_read_b128 v[90:93], v193 offset:34816
	ds_read_b128 v[174:177], v193 offset:35840
	ds_read_b128 v[178:181], v193 offset:36864
	ds_read_b128 v[214:217], v193 offset:37888
	ds_read_b128 v[218:221], v193 offset:38912
	ds_read_b128 v[222:225], v193 offset:39936
	global_load_lds_dwordx4 v[226:227], off
	v_lshl_add_u64 v[226:227], s[60:61], 0, v[196:197]
	s_mov_b32 m0, s69
	s_nop 0
	global_load_lds_dwordx4 v[226:227], off
	s_waitcnt vmcnt(8)
	s_waitcnt lgkmcnt(0)
	s_barrier
	s_setprio 1
	v_mfma_f32_16x16x32_bf16 v[150:153], v[50:53], v[74:77], v[150:153]
	v_mfma_f32_16x16x32_bf16 v[158:161], v[58:61], v[74:77], v[158:161]
	v_mfma_f32_16x16x32_bf16 v[134:137], v[50:53], v[90:93], v[134:137]
	v_mfma_f32_16x16x32_bf16 v[142:145], v[58:61], v[90:93], v[142:145]
	v_mfma_f32_16x16x32_bf16 v[118:121], v[50:53], v[178:181], v[118:121]
	v_mfma_f32_16x16x32_bf16 v[126:129], v[58:61], v[178:181], v[126:129]
	v_mfma_f32_16x16x32_bf16 v[110:113], v[50:53], v[218:221], v[110:113]
	v_mfma_f32_16x16x32_bf16 v[106:109], v[58:61], v[218:221], v[106:109]
	v_mfma_f32_16x16x32_bf16 v[150:153], v[54:57], v[82:85], v[150:153]
	v_mfma_f32_16x16x32_bf16 v[158:161], v[66:69], v[82:85], v[158:161]
	v_mfma_f32_16x16x32_bf16 v[134:137], v[54:57], v[174:177], v[134:137]
	v_mfma_f32_16x16x32_bf16 v[142:145], v[66:69], v[174:177], v[142:145]
	v_mfma_f32_16x16x32_bf16 v[118:121], v[54:57], v[214:217], v[118:121]
	v_mfma_f32_16x16x32_bf16 v[126:129], v[66:69], v[214:217], v[126:129]
	v_mfma_f32_16x16x32_bf16 v[110:113], v[54:57], v[222:225], v[110:113]
	v_mfma_f32_16x16x32_bf16 v[106:109], v[66:69], v[222:225], v[106:109]
	s_setprio 0
	s_setprio 1
	v_mfma_f32_16x16x32_bf16 v[146:149], v[70:73], v[74:77], v[146:149]
	v_mfma_f32_16x16x32_bf16 v[74:77], v[166:169], v[74:77], v[154:157]
	v_mfma_f32_16x16x32_bf16 v[154:157], v[170:173], v[82:85], v[74:77]
	v_mfma_f32_16x16x32_bf16 v[74:77], v[70:73], v[90:93], v[130:133]
	v_mfma_f32_16x16x32_bf16 v[130:133], v[162:165], v[174:177], v[74:77]
	v_mfma_f32_16x16x32_bf16 v[74:77], v[166:169], v[90:93], v[138:141]
	v_mfma_f32_16x16x32_bf16 v[138:141], v[170:173], v[174:177], v[74:77]
	v_mfma_f32_16x16x32_bf16 v[74:77], v[70:73], v[178:181], v[114:117]
	v_mfma_f32_16x16x32_bf16 v[114:117], v[162:165], v[214:217], v[74:77]
	v_mfma_f32_16x16x32_bf16 v[74:77], v[166:169], v[178:181], v[122:125]
	v_mfma_f32_16x16x32_bf16 v[122:125], v[170:173], v[214:217], v[74:77]
	v_mfma_f32_16x16x32_bf16 v[74:77], v[70:73], v[218:221], v[102:105]
	v_mfma_f32_16x16x32_bf16 v[102:105], v[162:165], v[222:225], v[74:77]
	v_mfma_f32_16x16x32_bf16 v[74:77], v[166:169], v[218:221], v[98:101]
	v_mfma_f32_16x16x32_bf16 v[146:149], v[162:165], v[82:85], v[146:149]
	v_mfma_f32_16x16x32_bf16 v[98:101], v[170:173], v[222:225], v[74:77]
	s_setprio 0
	s_barrier
; #define PG8_STAGE(bufoff, gbase) do { _Pragma("unroll") for (int _i = 0; _i < 2; ++_i) \
;         __builtin_amdgcn_global_load_lds((const unsigned*)((const char*)(gbase) + voff[_i]), (LAS unsigned*)(lds + (bufoff) + ldsw + _i * 8192), 16, 0, 0); } while (0)
; #define PG8_LDA(dst, b, h) do { _Pragma("unroll") for (int m = 0; m < 4; ++m) _Pragma("unroll") for (int k = 0; k < 2; ++k) dst[m][k] = *(const LAS bf16x8*)(lds + PG8_SA(b, h) + aoff + m * 2048 + k * 1024); } while (0)
; #define PG8_LDB(dst, b, h) do { _Pragma("unroll") for (int n = 0; n < 2; ++n) _Pragma("unroll") for (int k = 0; k < 2; ++k) dst[n][k] = *(const LAS bf16x8*)(lds + PG8_SB(b, h) + boff + n * 2048 + k * 1024); } while (0)
; #define PG8_WAIT_V(n) asm volatile("s_waitcnt vmcnt(" #n ")" ::: "memory")
; #define PG8_WAIT_L(n) asm volatile("s_waitcnt lgkmcnt(" #n ")" ::: "memory")
; #define PG8_BAR __builtin_amdgcn_s_barrier()
; #define PG8_SCHED __builtin_amdgcn_sched_barrier(0)
; template <int EPI> ...
;     ...
;         for (int t = 0; t < cnk; t += 2) {
;             const bool last = (t == cnk - 2);
;             const char* a1 = cA + (size_t)(t + 1) * kstep;
;             const char* a2 = last ? nA : cA + (size_t)(t + 2) * kstep; const char* b2 = last ? nB : cB + (size_t)(t + 2) * kstep;
;             const char* a3 = a2 + kstep; const char* b3 = b2 + kstep;
;             PG8_LDB(B0, 0, 0); PG8_LDB(B1, 0, 1); PG8_SCHED; PG8_LDA(At, 0, 0); PG8_STAGE(PG8_SA(1, 1), a1 + hstep);
;             PG8_WAIT_V(8); PG8_WAIT_L(0); PG8_BAR; PG8_MMA(0, 0, At, B0); PG8_MMA(0, 1, At, B1); PG8_BAR; PG8_SCHED;
;             PG8_LDA(At, 0, 1); PG8_STAGE(PG8_SB(0, 0), b2); PG8_STAGE(PG8_SB(0, 1), b2 + hstep); PG8_STAGE(PG8_SA(0, 0), a2);
;             PG8_WAIT_V(8); PG8_WAIT_L(0); PG8_BAR; PG8_MMA(1, 0, At, B0); PG8_MMA(1, 1, At, B1); PG8_BAR; PG8_SCHED;
;             PG8_LDB(B0, 1, 0); PG8_LDB(B1, 1, 1); PG8_SCHED; PG8_LDA(At, 1, 0); PG8_STAGE(PG8_SA(0, 1), a2 + hstep);
;             PG8_WAIT_V(8); PG8_WAIT_L(0); PG8_BAR; PG8_MMA(0, 0, At, B0); PG8_MMA(0, 1, At, B1); PG8_BAR; PG8_SCHED;
;             PG8_LDA(At, 1, 1); PG8_STAGE(PG8_SB(1, 0), b3); PG8_STAGE(PG8_SB(1, 1), b3 + hstep); PG8_STAGE(PG8_SA(1, 0), a3);
;             PG8_WAIT_V(8); PG8_WAIT_L(0); PG8_BAR; PG8_MMA(1, 0, At, B0); PG8_MMA(1, 1, At, B1); PG8_BAR; PG8_SCHED;
;         }
;         if (wr == 0) PG8_BAR;
	s_add_i32 s60, s84, s65
	v_lshl_add_u64 v[82:83], v[230:231], 0, s[26:27]
	s_mov_b32 m0, s60
	s_nop 0
	ds_read_b128 v[74:77], v193 offset:49152
	ds_read_b128 v[90:93], v193 offset:50176
	ds_read_b128 v[174:177], v193 offset:51200
	ds_read_b128 v[178:181], v193 offset:52224
	ds_read_b128 v[214:217], v193 offset:53248
	ds_read_b128 v[218:221], v193 offset:54272
	ds_read_b128 v[222:225], v193 offset:55296
	ds_read_b128 v[226:229], v193 offset:56320
	global_load_lds_dwordx4 v[82:83], off
	s_add_i32 m0, s60, 0x2000
	s_add_u32 s58, s58, 0x40080
	v_lshl_add_u64 v[82:83], v[232:233], 0, s[26:27]
	s_addc_u32 s59, s59, 0
	s_add_i32 s60, s85, s65
	global_load_lds_dwordx4 v[82:83], off
	v_lshl_add_u64 v[82:83], s[58:59], 0, v[194:195]
	s_mov_b32 m0, s60
	s_nop 0
	global_load_lds_dwordx4 v[82:83], off
	v_lshl_add_u64 v[82:83], s[58:59], 0, v[196:197]
	s_add_i32 m0, s60, 0x2000
	s_nop 0
	global_load_lds_dwordx4 v[82:83], off
	v_lshl_add_u64 v[82:83], v[234:235], 0, s[26:27]
	s_mov_b32 m0, s72
	s_nop 0
	global_load_lds_dwordx4 v[82:83], off
	v_lshl_add_u64 v[82:83], v[236:237], 0, s[26:27]
	s_mov_b32 m0, s73
	s_nop 0
	global_load_lds_dwordx4 v[82:83], off
	s_waitcnt vmcnt(8)
	s_waitcnt lgkmcnt(0)
	s_barrier
	s_setprio 1
	v_mfma_f32_16x16x32_bf16 v[82:85], v[50:53], v[74:77], v[86:89]
	v_mfma_f32_16x16x32_bf16 v[86:89], v[54:57], v[90:93], v[82:85]
	v_mfma_f32_16x16x32_bf16 v[82:85], v[58:61], v[74:77], v[94:97]
	v_mfma_f32_16x16x32_bf16 v[62:65], v[50:53], v[174:177], v[62:65]
	v_mfma_f32_16x16x32_bf16 v[78:81], v[58:61], v[174:177], v[78:81]
	v_mfma_f32_16x16x32_bf16 v[22:25], v[50:53], v[214:217], v[22:25]
	v_mfma_f32_16x16x32_bf16 v[30:33], v[58:61], v[214:217], v[30:33]
	v_mfma_f32_16x16x32_bf16 v[14:17], v[50:53], v[222:225], v[14:17]
	v_mfma_f32_16x16x32_bf16 v[10:13], v[58:61], v[222:225], v[10:13]
	v_mfma_f32_16x16x32_bf16 v[94:97], v[66:69], v[90:93], v[82:85]
	v_mfma_f32_16x16x32_bf16 v[62:65], v[54:57], v[178:181], v[62:65]
	v_mfma_f32_16x16x32_bf16 v[78:81], v[66:69], v[178:181], v[78:81]
	v_mfma_f32_16x16x32_bf16 v[22:25], v[54:57], v[218:221], v[22:25]
	v_mfma_f32_16x16x32_bf16 v[30:33], v[66:69], v[218:221], v[30:33]
	v_mfma_f32_16x16x32_bf16 v[14:17], v[54:57], v[226:229], v[14:17]
	v_mfma_f32_16x16x32_bf16 v[10:13], v[66:69], v[226:229], v[10:13]
	s_setprio 0
	s_setprio 1
	v_mfma_f32_16x16x32_bf16 v[38:41], v[70:73], v[74:77], v[38:41]
	v_mfma_f32_16x16x32_bf16 v[82:85], v[162:165], v[90:93], v[38:41]
	v_mfma_f32_16x16x32_bf16 v[38:41], v[166:169], v[74:77], v[42:45]
	v_mfma_f32_16x16x32_bf16 v[90:93], v[170:173], v[90:93], v[38:41]
	v_mfma_f32_16x16x32_bf16 v[34:37], v[70:73], v[174:177], v[34:37]
	v_mfma_f32_16x16x32_bf16 v[38:41], v[166:169], v[174:177], v[46:49]
	v_mfma_f32_16x16x32_bf16 v[18:21], v[70:73], v[214:217], v[18:21]
	v_mfma_f32_16x16x32_bf16 v[26:29], v[166:169], v[214:217], v[26:29]
	v_mfma_f32_16x16x32_bf16 v[6:9], v[70:73], v[222:225], v[6:9]
	v_mfma_f32_16x16x32_bf16 v[2:5], v[166:169], v[222:225], v[2:5]
	v_mfma_f32_16x16x32_bf16 v[34:37], v[162:165], v[178:181], v[34:37]
	v_mfma_f32_16x16x32_bf16 v[74:77], v[170:173], v[178:181], v[38:41]
	v_mfma_f32_16x16x32_bf16 v[18:21], v[162:165], v[218:221], v[18:21]
	v_mfma_f32_16x16x32_bf16 v[26:29], v[170:173], v[218:221], v[26:29]
	v_mfma_f32_16x16x32_bf16 v[6:9], v[162:165], v[226:229], v[6:9]
	v_mfma_f32_16x16x32_bf16 v[2:5], v[170:173], v[226:229], v[2:5]
	s_setprio 0
	s_barrier
	s_add_i32 s83, s83, 2
	s_add_u32 s56, s56, 0x100
	s_addc_u32 s57, s57, 0
	s_add_u32 s62, s62, 0x100
	s_addc_u32 s63, s63, 0
	s_cmp_gt_u32 s83, 13
	s_cbranch_scc0 .LBB0_970
	s_and_b64 vcc, exec, s[28:29]
	s_cbranch_vccz .LBB0_973
	s_barrier

; #define PG8_STAGE(bufoff, gbase) do { _Pragma("unroll") for (int _i = 0; _i < 2; ++_i) \
;         __builtin_amdgcn_global_load_lds((const unsigned*)((const char*)(gbase) + voff[_i]), (LAS unsigned*)(lds + (bufoff) + ldsw + _i * 8192), 16, 0, 0); } while (0)
; #define PG8_LDA(dst, b, h) do { _Pragma("unroll") for (int m = 0; m < 4; ++m) _Pragma("unroll") for (int k = 0; k < 2; ++k) dst[m][k] = *(const LAS bf16x8*)(lds + PG8_SA(b, h) + aoff + m * 2048 + k * 1024); } while (0)
; #define PG8_LDB(dst, b, h) do { _Pragma("unroll") for (int n = 0; n < 2; ++n) _Pragma("unroll") for (int k = 0; k < 2; ++k) dst[n][k] = *(const LAS bf16x8*)(lds + PG8_SB(b, h) + boff + n * 2048 + k * 1024); } while (0)
; #define PG8_MMA(ai, bj, At, Bt) do { __builtin_amdgcn_s_setprio(1); _Pragma("unroll") for (int m = 0; m < 4; ++m) _Pragma("unroll") for (int n = 0; n < 2; ++n) _Pragma("unroll") for (int k = 0; k < 2; ++k) \
;         acc[ai][bj][m][n] = __builtin_amdgcn_mfma_f32_16x16x32_bf16(Bt[n][k], At[m][k], acc[ai][bj][m][n], 0, 0, 0); __builtin_amdgcn_s_setprio(0); } while (0)
; #define PG8_WAIT_V(n) asm volatile("s_waitcnt vmcnt(" #n ")" ::: "memory")
; #define PG8_WAIT_L(n) asm volatile("s_waitcnt lgkmcnt(" #n ")" ::: "memory")
; #define PG8_BAR __builtin_amdgcn_s_barrier()
; template <int EPI> ...
;     ...
;         for (int t = 0; t < cnk; t += 2) {
;             const bool last = (t == cnk - 2);
;             const char* a1 = cA + (size_t)(t + 1) * kstep;
;             const char* a2 = last ? nA : cA + (size_t)(t + 2) * kstep; const char* b2 = last ? nB : cB + (size_t)(t + 2) * kstep;
;             const char* a3 = a2 + kstep; const char* b3 = b2 + kstep;
;             PG8_LDB(B0, 0, 0); PG8_LDB(B1, 0, 1); PG8_SCHED; PG8_LDA(At, 0, 0); PG8_STAGE(PG8_SA(1, 1), a1 + hstep);
;             PG8_WAIT_V(8); PG8_WAIT_L(0); PG8_BAR; PG8_MMA(0, 0, At, B0); PG8_MMA(0, 1, At, B1); PG8_BAR; PG8_SCHED;
;             PG8_LDA(At, 0, 1); PG8_STAGE(PG8_SB(0, 0), b2); PG8_STAGE(PG8_SB(0, 1), b2 + hstep); PG8_STAGE(PG8_SA(0, 0), a2);
;             PG8_WAIT_V(8); PG8_WAIT_L(0); PG8_BAR; PG8_MMA(1, 0, At, B0); PG8_MMA(1, 1, At, B1); PG8_BAR; PG8_SCHED;
;             PG8_LDB(B0, 1, 0); PG8_LDB(B1, 1, 1); PG8_SCHED; PG8_LDA(At, 1, 0); PG8_STAGE(PG8_SA(0, 1), a2 + hstep);
;             PG8_WAIT_V(8); PG8_WAIT_L(0); PG8_BAR; PG8_MMA(0, 0, At, B0); PG8_MMA(0, 1, At, B1); PG8_BAR; PG8_SCHED;
.LBB0_1246:
	ds_read_b128 v[128:131], v156
	ds_read_b128 v[132:135], v156 offset:1024
	ds_read_b128 v[148:151], v156 offset:2048
	ds_read_b128 v[160:163], v156 offset:3072
	ds_read_b128 v[164:167], v157
	ds_read_b128 v[168:171], v157 offset:1024
	ds_read_b128 v[172:175], v157 offset:2048
	ds_read_b128 v[176:179], v157 offset:3072
	s_add_i32 s57, s28, 2
	s_add_u32 s26, s24, 0x100
	s_addc_u32 s27, s25, 0
	s_cmp_eq_u32 s54, s28
	s_cselect_b32 s28, s18, s55
	s_cselect_b32 s31, s17, s27
	s_cselect_b32 s30, s16, s26
	s_cselect_b32 s29, s19, s56
	v_lshl_add_u64 v[180:181], s[24:25], 0, v[142:143]
	s_add_i32 m0, s38, 0xc000
	ds_read_b128 v[194:197], v158
	ds_read_b128 v[198:201], v158 offset:1024
	ds_read_b128 v[202:205], v158 offset:2048
	ds_read_b128 v[206:209], v158 offset:3072
	ds_read_b128 v[210:213], v158 offset:4096
	ds_read_b128 v[214:217], v158 offset:5120
	ds_read_b128 v[218:221], v158 offset:6144
	ds_read_b128 v[222:225], v158 offset:7168
	global_load_lds_dwordx4 v[180:181], off
	v_lshl_add_u64 v[180:181], s[24:25], 0, v[144:145]
	s_add_i32 m0, s38, 0xe000
	s_nop 0
	global_load_lds_dwordx4 v[180:181], off
	s_waitcnt vmcnt(8)
	s_waitcnt lgkmcnt(0)
	s_barrier
	s_setprio 1
	v_mfma_f32_16x16x32_bf16 v[124:127], v[128:131], v[194:197], v[124:127]
	v_mfma_f32_16x16x32_bf16 v[120:123], v[148:151], v[194:197], v[120:123]
	v_mfma_f32_16x16x32_bf16 v[116:119], v[128:131], v[202:205], v[116:119]
	v_mfma_f32_16x16x32_bf16 v[112:115], v[148:151], v[202:205], v[112:115]
	v_mfma_f32_16x16x32_bf16 v[104:107], v[128:131], v[210:213], v[104:107]
	v_mfma_f32_16x16x32_bf16 v[96:99], v[148:151], v[210:213], v[96:99]
	v_mfma_f32_16x16x32_bf16 v[88:91], v[128:131], v[218:221], v[88:91]
	v_mfma_f32_16x16x32_bf16 v[80:83], v[148:151], v[218:221], v[80:83]
	v_mfma_f32_16x16x32_bf16 v[124:127], v[132:135], v[198:201], v[124:127]
	v_mfma_f32_16x16x32_bf16 v[120:123], v[160:163], v[198:201], v[120:123]
	v_mfma_f32_16x16x32_bf16 v[116:119], v[132:135], v[206:209], v[116:119]
	v_mfma_f32_16x16x32_bf16 v[112:115], v[160:163], v[206:209], v[112:115]
	v_mfma_f32_16x16x32_bf16 v[104:107], v[132:135], v[214:217], v[104:107]
	v_mfma_f32_16x16x32_bf16 v[96:99], v[160:163], v[214:217], v[96:99]
	v_mfma_f32_16x16x32_bf16 v[88:91], v[132:135], v[222:225], v[88:91]
	v_mfma_f32_16x16x32_bf16 v[80:83], v[160:163], v[222:225], v[80:83]
	s_setprio 0
	s_setprio 1
	v_mfma_f32_16x16x32_bf16 v[108:111], v[164:167], v[194:197], v[108:111]
	v_mfma_f32_16x16x32_bf16 v[100:103], v[172:175], v[194:197], v[100:103]
	v_mfma_f32_16x16x32_bf16 v[92:95], v[164:167], v[202:205], v[92:95]
	v_mfma_f32_16x16x32_bf16 v[84:87], v[172:175], v[202:205], v[84:87]
	v_mfma_f32_16x16x32_bf16 v[76:79], v[164:167], v[210:213], v[76:79]
	v_mfma_f32_16x16x32_bf16 v[72:75], v[172:175], v[210:213], v[72:75]
	v_mfma_f32_16x16x32_bf16 v[68:71], v[164:167], v[218:221], v[68:71]
	v_mfma_f32_16x16x32_bf16 v[64:67], v[172:175], v[218:221], v[64:67]
	v_mfma_f32_16x16x32_bf16 v[108:111], v[168:171], v[198:201], v[108:111]
	v_mfma_f32_16x16x32_bf16 v[100:103], v[176:179], v[198:201], v[100:103]
	v_mfma_f32_16x16x32_bf16 v[92:95], v[168:171], v[206:209], v[92:95]
	v_mfma_f32_16x16x32_bf16 v[84:87], v[176:179], v[206:209], v[84:87]
	v_mfma_f32_16x16x32_bf16 v[76:79], v[168:171], v[214:217], v[76:79]
	v_mfma_f32_16x16x32_bf16 v[72:75], v[176:179], v[214:217], v[72:75]
	v_mfma_f32_16x16x32_bf16 v[68:71], v[168:171], v[222:225], v[68:71]
	v_mfma_f32_16x16x32_bf16 v[64:67], v[176:179], v[222:225], v[64:67]
	s_setprio 0
	s_barrier
	s_add_i32 s24, s45, s37
	v_lshl_add_u64 v[180:181], s[28:29], 0, v[136:137]
	s_mov_b32 m0, s24
	ds_read_b128 v[194:197], v158 offset:16384
	ds_read_b128 v[198:201], v158 offset:17408
	ds_read_b128 v[202:205], v158 offset:18432
	ds_read_b128 v[206:209], v158 offset:19456
	ds_read_b128 v[210:213], v158 offset:20480
	ds_read_b128 v[214:217], v158 offset:21504
	ds_read_b128 v[218:221], v158 offset:22528
	ds_read_b128 v[222:225], v158 offset:23552
	global_load_lds_dwordx4 v[180:181], off
	s_add_i32 m0, s24, 0x2000
	s_add_u32 s24, s28, 0xb0000
	v_lshl_add_u64 v[186:187], s[28:29], 0, v[138:139]
	s_addc_u32 s25, s29, 0
	s_add_i32 s58, s46, s37
	global_load_lds_dwordx4 v[186:187], off
	v_lshl_add_u64 v[226:227], s[24:25], 0, v[136:137]
	s_mov_b32 m0, s58
	v_lshl_add_u64 v[228:229], s[30:31], 0, v[138:139]
	global_load_lds_dwordx4 v[226:227], off
	v_lshl_add_u64 v[226:227], s[24:25], 0, v[138:139]
	s_add_i32 m0, s58, 0x2000
	s_nop 0
	global_load_lds_dwordx4 v[226:227], off
	v_lshl_add_u64 v[226:227], s[30:31], 0, v[136:137]
	s_mov_b32 m0, s38
	s_nop 0
	global_load_lds_dwordx4 v[226:227], off
	s_mov_b32 m0, s39
	s_nop 0
	global_load_lds_dwordx4 v[228:229], off
	s_waitcnt vmcnt(8)
	s_waitcnt lgkmcnt(0)
	s_barrier
; #define PG8_STAGE(bufoff, gbase) do { _Pragma("unroll") for (int _i = 0; _i < 2; ++_i) \
;         __builtin_amdgcn_global_load_lds((const unsigned*)((const char*)(gbase) + voff[_i]), (LAS unsigned*)(lds + (bufoff) + ldsw + _i * 8192), 16, 0, 0); } while (0)
; #define PG8_LDA(dst, b, h) do { _Pragma("unroll") for (int m = 0; m < 4; ++m) _Pragma("unroll") for (int k = 0; k < 2; ++k) dst[m][k] = *(const LAS bf16x8*)(lds + PG8_SA(b, h) + aoff + m * 2048 + k * 1024); } while (0)
; #define PG8_LDB(dst, b, h) do { _Pragma("unroll") for (int n = 0; n < 2; ++n) _Pragma("unroll") for (int k = 0; k < 2; ++k) dst[n][k] = *(const LAS bf16x8*)(lds + PG8_SB(b, h) + boff + n * 2048 + k * 1024); } while (0)
; #define PG8_MMA(ai, bj, At, Bt) do { __builtin_amdgcn_s_setprio(1); _Pragma("unroll") for (int m = 0; m < 4; ++m) _Pragma("unroll") for (int n = 0; n < 2; ++n) _Pragma("unroll") for (int k = 0; k < 2; ++k) \
;         acc[ai][bj][m][n] = __builtin_amdgcn_mfma_f32_16x16x32_bf16(Bt[n][k], At[m][k], acc[ai][bj][m][n], 0, 0, 0); __builtin_amdgcn_s_setprio(0); } while (0)
; #define PG8_WAIT_V(n) asm volatile("s_waitcnt vmcnt(" #n ")" ::: "memory")
; #define PG8_WAIT_L(n) asm volatile("s_waitcnt lgkmcnt(" #n ")" ::: "memory")
; #define PG8_BAR __builtin_amdgcn_s_barrier()
; #define PG8_SCHED __builtin_amdgcn_sched_barrier(0)
; template <int EPI> ...
;     ...
;             PG8_LDA(At, 0, 1); PG8_STAGE(PG8_SB(0, 0), b2); PG8_STAGE(PG8_SB(0, 1), b2 + hstep); PG8_STAGE(PG8_SA(0, 0), a2);
;             PG8_WAIT_V(8); PG8_WAIT_L(0); PG8_BAR; PG8_MMA(1, 0, At, B0); PG8_MMA(1, 1, At, B1); PG8_BAR; PG8_SCHED;
;             PG8_LDB(B0, 1, 0); PG8_LDB(B1, 1, 1); PG8_SCHED; PG8_LDA(At, 1, 0); PG8_STAGE(PG8_SA(0, 1), a2 + hstep);
;             PG8_WAIT_V(8); PG8_WAIT_L(0); PG8_BAR; PG8_MMA(0, 0, At, B0); PG8_MMA(0, 1, At, B1); PG8_BAR; PG8_SCHED;
;             PG8_LDA(At, 1, 1); PG8_STAGE(PG8_SB(1, 0), b3); PG8_STAGE(PG8_SB(1, 1), b3 + hstep); PG8_STAGE(PG8_SA(1, 0), a3);
;             PG8_WAIT_V(8); PG8_WAIT_L(0); PG8_BAR; PG8_MMA(1, 0, At, B0); PG8_MMA(1, 1, At, B1); PG8_BAR; PG8_SCHED;
	s_setprio 1
	v_mfma_f32_16x16x32_bf16 v[60:63], v[128:131], v[194:197], v[60:63]
	v_mfma_f32_16x16x32_bf16 v[56:59], v[148:151], v[194:197], v[56:59]
	v_mfma_f32_16x16x32_bf16 v[52:55], v[128:131], v[202:205], v[52:55]
	v_mfma_f32_16x16x32_bf16 v[48:51], v[148:151], v[202:205], v[48:51]
	v_mfma_f32_16x16x32_bf16 v[40:43], v[128:131], v[210:213], v[40:43]
	v_mfma_f32_16x16x32_bf16 v[32:35], v[148:151], v[210:213], v[32:35]
	v_mfma_f32_16x16x32_bf16 v[24:27], v[128:131], v[218:221], v[24:27]
	v_mfma_f32_16x16x32_bf16 v[16:19], v[148:151], v[218:221], v[16:19]
	v_mfma_f32_16x16x32_bf16 v[60:63], v[132:135], v[198:201], v[60:63]
	v_mfma_f32_16x16x32_bf16 v[56:59], v[160:163], v[198:201], v[56:59]
	v_mfma_f32_16x16x32_bf16 v[52:55], v[132:135], v[206:209], v[52:55]
	v_mfma_f32_16x16x32_bf16 v[48:51], v[160:163], v[206:209], v[48:51]
	v_mfma_f32_16x16x32_bf16 v[40:43], v[132:135], v[214:217], v[40:43]
	v_mfma_f32_16x16x32_bf16 v[32:35], v[160:163], v[214:217], v[32:35]
	v_mfma_f32_16x16x32_bf16 v[24:27], v[132:135], v[222:225], v[24:27]
	v_mfma_f32_16x16x32_bf16 v[16:19], v[160:163], v[222:225], v[16:19]
	s_setprio 0
	s_setprio 1
	v_mfma_f32_16x16x32_bf16 v[44:47], v[164:167], v[194:197], v[44:47]
	v_mfma_f32_16x16x32_bf16 v[36:39], v[172:175], v[194:197], v[36:39]
	v_mfma_f32_16x16x32_bf16 v[28:31], v[164:167], v[202:205], v[28:31]
	v_mfma_f32_16x16x32_bf16 v[20:23], v[172:175], v[202:205], v[20:23]
	v_mfma_f32_16x16x32_bf16 v[12:15], v[164:167], v[210:213], v[12:15]
	v_mfma_f32_16x16x32_bf16 v[8:11], v[172:175], v[210:213], v[8:11]
	v_mfma_f32_16x16x32_bf16 v[4:7], v[164:167], v[218:221], v[4:7]
	v_mfma_f32_16x16x32_bf16 v[0:3], v[172:175], v[218:221], v[0:3]
	v_mfma_f32_16x16x32_bf16 v[44:47], v[168:171], v[198:201], v[44:47]
	v_mfma_f32_16x16x32_bf16 v[36:39], v[176:179], v[198:201], v[36:39]
	v_mfma_f32_16x16x32_bf16 v[28:31], v[168:171], v[206:209], v[28:31]
	v_mfma_f32_16x16x32_bf16 v[20:23], v[176:179], v[206:209], v[20:23]
	v_mfma_f32_16x16x32_bf16 v[12:15], v[168:171], v[214:217], v[12:15]
	v_mfma_f32_16x16x32_bf16 v[8:11], v[176:179], v[214:217], v[8:11]
	v_mfma_f32_16x16x32_bf16 v[4:7], v[168:171], v[222:225], v[4:7]
	v_mfma_f32_16x16x32_bf16 v[0:3], v[176:179], v[222:225], v[0:3]
	s_setprio 0
	s_barrier
	s_add_i32 s58, 0, 0x18000
	v_add_u32_e32 v159, s58, v153
	s_add_i32 s59, 0, 0x1c000
	ds_read_b128 v[128:131], v159
	ds_read_b128 v[132:135], v159 offset:1024
	ds_read_b128 v[148:151], v159 offset:2048
	ds_read_b128 v[160:163], v159 offset:3072
	v_add_u32_e32 v159, s59, v153
	ds_read_b128 v[164:167], v159
	ds_read_b128 v[168:171], v159 offset:1024
	ds_read_b128 v[172:175], v159 offset:2048
	ds_read_b128 v[176:179], v159 offset:3072
	s_add_u32 s24, s30, 0xb0000
	s_addc_u32 s25, s31, 0
	s_mov_b32 m0, s40
	v_lshl_add_u64 v[230:231], s[24:25], 0, v[136:137]
	ds_read_b128 v[194:197], v158 offset:32768
	ds_read_b128 v[198:201], v158 offset:33792
	ds_read_b128 v[202:205], v158 offset:34816
	ds_read_b128 v[206:209], v158 offset:35840
	ds_read_b128 v[210:213], v158 offset:36864
	ds_read_b128 v[214:217], v158 offset:37888
	ds_read_b128 v[218:221], v158 offset:38912
	ds_read_b128 v[222:225], v158 offset:39936
	global_load_lds_dwordx4 v[230:231], off
	v_lshl_add_u64 v[230:231], s[24:25], 0, v[138:139]
	s_mov_b32 m0, s41
	s_nop 0
	global_load_lds_dwordx4 v[230:231], off
	s_waitcnt vmcnt(8)
	s_waitcnt lgkmcnt(0)
	s_barrier
	s_setprio 1
	v_mfma_f32_16x16x32_bf16 v[124:127], v[128:131], v[194:197], v[124:127]
	v_mfma_f32_16x16x32_bf16 v[120:123], v[148:151], v[194:197], v[120:123]
	v_mfma_f32_16x16x32_bf16 v[116:119], v[128:131], v[202:205], v[116:119]
	v_mfma_f32_16x16x32_bf16 v[112:115], v[148:151], v[202:205], v[112:115]
	v_mfma_f32_16x16x32_bf16 v[104:107], v[128:131], v[210:213], v[104:107]
	v_mfma_f32_16x16x32_bf16 v[96:99], v[148:151], v[210:213], v[96:99]
	v_mfma_f32_16x16x32_bf16 v[88:91], v[128:131], v[218:221], v[88:91]
	v_mfma_f32_16x16x32_bf16 v[80:83], v[148:151], v[218:221], v[80:83]
	v_mfma_f32_16x16x32_bf16 v[124:127], v[132:135], v[198:201], v[124:127]
	v_mfma_f32_16x16x32_bf16 v[120:123], v[160:163], v[198:201], v[120:123]
	v_mfma_f32_16x16x32_bf16 v[116:119], v[132:135], v[206:209], v[116:119]
	v_mfma_f32_16x16x32_bf16 v[112:115], v[160:163], v[206:209], v[112:115]
	v_mfma_f32_16x16x32_bf16 v[104:107], v[132:135], v[214:217], v[104:107]
	v_mfma_f32_16x16x32_bf16 v[96:99], v[160:163], v[214:217], v[96:99]
	v_mfma_f32_16x16x32_bf16 v[88:91], v[132:135], v[222:225], v[88:91]
	v_mfma_f32_16x16x32_bf16 v[80:83], v[160:163], v[222:225], v[80:83]
	s_setprio 0
	s_setprio 1
	v_mfma_f32_16x16x32_bf16 v[108:111], v[164:167], v[194:197], v[108:111]
	v_mfma_f32_16x16x32_bf16 v[100:103], v[172:175], v[194:197], v[100:103]
	v_mfma_f32_16x16x32_bf16 v[92:95], v[164:167], v[202:205], v[92:95]
	v_mfma_f32_16x16x32_bf16 v[84:87], v[172:175], v[202:205], v[84:87]
	v_mfma_f32_16x16x32_bf16 v[76:79], v[164:167], v[210:213], v[76:79]
	v_mfma_f32_16x16x32_bf16 v[72:75], v[172:175], v[210:213], v[72:75]
	v_mfma_f32_16x16x32_bf16 v[68:71], v[164:167], v[218:221], v[68:71]
	v_mfma_f32_16x16x32_bf16 v[64:67], v[172:175], v[218:221], v[64:67]
	v_mfma_f32_16x16x32_bf16 v[108:111], v[168:171], v[198:201], v[108:111]
	v_mfma_f32_16x16x32_bf16 v[100:103], v[176:179], v[198:201], v[100:103]
	v_mfma_f32_16x16x32_bf16 v[92:95], v[168:171], v[206:209], v[92:95]
	v_mfma_f32_16x16x32_bf16 v[84:87], v[176:179], v[206:209], v[84:87]
	v_mfma_f32_16x16x32_bf16 v[76:79], v[168:171], v[214:217], v[76:79]
	v_mfma_f32_16x16x32_bf16 v[72:75], v[176:179], v[214:217], v[72:75]
	v_mfma_f32_16x16x32_bf16 v[68:71], v[168:171], v[222:225], v[68:71]
	v_mfma_f32_16x16x32_bf16 v[64:67], v[176:179], v[222:225], v[64:67]
	s_setprio 0
	s_barrier
; #define PG8_STAGE(bufoff, gbase) do { _Pragma("unroll") for (int _i = 0; _i < 2; ++_i) \
;         __builtin_amdgcn_global_load_lds((const unsigned*)((const char*)(gbase) + voff[_i]), (LAS unsigned*)(lds + (bufoff) + ldsw + _i * 8192), 16, 0, 0); } while (0)
; #define PG8_LDA(dst, b, h) do { _Pragma("unroll") for (int m = 0; m < 4; ++m) _Pragma("unroll") for (int k = 0; k < 2; ++k) dst[m][k] = *(const LAS bf16x8*)(lds + PG8_SA(b, h) + aoff + m * 2048 + k * 1024); } while (0)
; #define PG8_MMA(ai, bj, At, Bt) do { __builtin_amdgcn_s_setprio(1); _Pragma("unroll") for (int m = 0; m < 4; ++m) _Pragma("unroll") for (int n = 0; n < 2; ++n) _Pragma("unroll") for (int k = 0; k < 2; ++k) \
;         acc[ai][bj][m][n] = __builtin_amdgcn_mfma_f32_16x16x32_bf16(Bt[n][k], At[m][k], acc[ai][bj][m][n], 0, 0, 0); __builtin_amdgcn_s_setprio(0); } while (0)
; #define PG8_WAIT_V(n) asm volatile("s_waitcnt vmcnt(" #n ")" ::: "memory")
; #define PG8_WAIT_L(n) asm volatile("s_waitcnt lgkmcnt(" #n ")" ::: "memory")
; #define PG8_BAR __builtin_amdgcn_s_barrier()
; #define PG8_SCHED __builtin_amdgcn_sched_barrier(0)
; template <int EPI> ...
;     ...
;             PG8_LDA(At, 1, 1); PG8_STAGE(PG8_SB(1, 0), b3); PG8_STAGE(PG8_SB(1, 1), b3 + hstep); PG8_STAGE(PG8_SA(1, 0), a3);
;             PG8_WAIT_V(8); PG8_WAIT_L(0); PG8_BAR; PG8_MMA(1, 0, At, B0); PG8_MMA(1, 1, At, B1); PG8_BAR; PG8_SCHED;
;         }
;         if (wr == 0) PG8_BAR;
;         if (SPLIT && cur_slice >= 0) {
	s_add_i32 s24, s58, s37
	v_lshl_add_u64 v[180:181], v[180:181], 0, s[10:11]
	s_mov_b32 m0, s24
	ds_read_b128 v[194:197], v158 offset:49152
	ds_read_b128 v[198:201], v158 offset:50176
	ds_read_b128 v[202:205], v158 offset:51200
	ds_read_b128 v[206:209], v158 offset:52224
	ds_read_b128 v[210:213], v158 offset:53248
	ds_read_b128 v[214:217], v158 offset:54272
	ds_read_b128 v[218:221], v158 offset:55296
	ds_read_b128 v[222:225], v158 offset:56320
	global_load_lds_dwordx4 v[180:181], off
	s_add_i32 m0, s24, 0x2000
	s_add_u32 s24, s28, 0xb0080
	v_lshl_add_u64 v[180:181], v[186:187], 0, s[10:11]
	s_addc_u32 s25, s29, 0
	s_add_i32 s28, s59, s37
	global_load_lds_dwordx4 v[180:181], off
	v_lshl_add_u64 v[180:181], s[24:25], 0, v[136:137]
	s_mov_b32 m0, s28
	s_nop 0
	global_load_lds_dwordx4 v[180:181], off
	v_lshl_add_u64 v[180:181], s[24:25], 0, v[138:139]
	s_add_i32 m0, s28, 0x2000
	s_nop 0
	global_load_lds_dwordx4 v[180:181], off
	v_lshl_add_u64 v[180:181], v[226:227], 0, s[10:11]
	s_mov_b32 m0, s42
	s_nop 0
	global_load_lds_dwordx4 v[180:181], off
	v_lshl_add_u64 v[180:181], v[228:229], 0, s[10:11]
	s_mov_b32 m0, s43
	s_nop 0
	global_load_lds_dwordx4 v[180:181], off
	s_waitcnt vmcnt(8)
	s_waitcnt lgkmcnt(0)
	s_barrier
	s_setprio 1
	v_mfma_f32_16x16x32_bf16 v[60:63], v[128:131], v[194:197], v[60:63]
	v_mfma_f32_16x16x32_bf16 v[56:59], v[148:151], v[194:197], v[56:59]
	v_mfma_f32_16x16x32_bf16 v[52:55], v[128:131], v[202:205], v[52:55]
	v_mfma_f32_16x16x32_bf16 v[48:51], v[148:151], v[202:205], v[48:51]
	v_mfma_f32_16x16x32_bf16 v[40:43], v[128:131], v[210:213], v[40:43]
	v_mfma_f32_16x16x32_bf16 v[32:35], v[148:151], v[210:213], v[32:35]
	v_mfma_f32_16x16x32_bf16 v[24:27], v[128:131], v[218:221], v[24:27]
	v_mfma_f32_16x16x32_bf16 v[16:19], v[148:151], v[218:221], v[16:19]
	v_mfma_f32_16x16x32_bf16 v[60:63], v[132:135], v[198:201], v[60:63]
	v_mfma_f32_16x16x32_bf16 v[56:59], v[160:163], v[198:201], v[56:59]
	v_mfma_f32_16x16x32_bf16 v[52:55], v[132:135], v[206:209], v[52:55]
	v_mfma_f32_16x16x32_bf16 v[48:51], v[160:163], v[206:209], v[48:51]
	v_mfma_f32_16x16x32_bf16 v[40:43], v[132:135], v[214:217], v[40:43]
	v_mfma_f32_16x16x32_bf16 v[32:35], v[160:163], v[214:217], v[32:35]
	v_mfma_f32_16x16x32_bf16 v[24:27], v[132:135], v[222:225], v[24:27]
	v_mfma_f32_16x16x32_bf16 v[16:19], v[160:163], v[222:225], v[16:19]
	s_setprio 0
	s_setprio 1
	v_mfma_f32_16x16x32_bf16 v[44:47], v[164:167], v[194:197], v[44:47]
	v_mfma_f32_16x16x32_bf16 v[36:39], v[172:175], v[194:197], v[36:39]
	v_mfma_f32_16x16x32_bf16 v[28:31], v[164:167], v[202:205], v[28:31]
	v_mfma_f32_16x16x32_bf16 v[20:23], v[172:175], v[202:205], v[20:23]
	v_mfma_f32_16x16x32_bf16 v[12:15], v[164:167], v[210:213], v[12:15]
	v_mfma_f32_16x16x32_bf16 v[8:11], v[172:175], v[210:213], v[8:11]
	v_mfma_f32_16x16x32_bf16 v[4:7], v[164:167], v[218:221], v[4:7]
	v_mfma_f32_16x16x32_bf16 v[0:3], v[172:175], v[218:221], v[0:3]
	v_mfma_f32_16x16x32_bf16 v[44:47], v[168:171], v[198:201], v[44:47]
	v_mfma_f32_16x16x32_bf16 v[36:39], v[176:179], v[198:201], v[36:39]
	v_mfma_f32_16x16x32_bf16 v[28:31], v[168:171], v[206:209], v[28:31]
	v_mfma_f32_16x16x32_bf16 v[20:23], v[176:179], v[206:209], v[20:23]
	v_mfma_f32_16x16x32_bf16 v[12:15], v[168:171], v[214:217], v[12:15]
	v_mfma_f32_16x16x32_bf16 v[8:11], v[176:179], v[214:217], v[8:11]
	v_mfma_f32_16x16x32_bf16 v[4:7], v[168:171], v[222:225], v[4:7]
	v_mfma_f32_16x16x32_bf16 v[0:3], v[176:179], v[222:225], v[0:3]
	s_setprio 0
	s_barrier
	s_add_u32 s55, s55, 0x100
	s_addc_u32 s56, s56, 0
	s_cmp_ge_u32 s57, s53
	s_mov_b64 s[24:25], s[26:27]
	s_mov_b32 s28, s57
	s_cbranch_scc0 .LBB0_1246
	s_and_b64 vcc, exec, s[12:13]
	s_cbranch_vccz .LBB0_1251
	s_barrier
	s_cmp_lt_i32 s2, 0
	s_mov_b64 s[24:25], -1
	s_cbranch_scc1 .LBB0_1252
